# GEMM K-loops: LDS-DMA addresses via SGPR base + 32-bit VGPR offset (no 64-bit VALU adds in load segments)
# baseline (speedup 1.0000x reference)
; #define PG8_STAGE(bufoff, gbase, voff) do { _Pragma("unroll") for (int _i = 0; _i < 2; ++_i) \
;         __builtin_amdgcn_global_load_lds((const unsigned*)((const char*)(gbase) + (voff)[_i]), (PG8_LAS unsigned*)(lds + (bufoff) + ldsw + _i * 8192), 16, 0, 0); } while (0)
; #define PG8_LDA(dst, b, h) do { _Pragma("unroll") for (int m = 0; m < 4; ++m) _Pragma("unroll") for (int k = 0; k < 2; ++k) dst[m][k] = *(const PG8_LAS bf16x8*)(lds + PG8_SA(b, h) + aoff + m * 2048 + k * 1024); } while (0)
; #define PG8_LDB(dst, b, h) do { _Pragma("unroll") for (int n = 0; n < 2; ++n) _Pragma("unroll") for (int k = 0; k < 2; ++k) dst[n][k] = *(const PG8_LAS bf16x8*)(lds + PG8_SB(b, h) + boff + n * 2048 + k * 1024); } while (0)
; #define PG8_MMA(ai, bj, At, Bt) do { __builtin_amdgcn_s_setprio(1); _Pragma("unroll") for (int m = 0; m < 4; ++m) _Pragma("unroll") for (int n = 0; n < 2; ++n) _Pragma("unroll") for (int k = 0; k < 2; ++k) \
;         acc[ai][bj][m][n] = __builtin_amdgcn_mfma_f32_16x16x32_bf16(Bt[n][k], At[m][k], acc[ai][bj][m][n], 0, 0, 0); __builtin_amdgcn_s_setprio(0); } while (0)
; #define PG8_WAIT_V(n) asm volatile("s_waitcnt vmcnt(" #n ")" ::: "memory")
; #define PG8_WAIT_L(n) asm volatile("s_waitcnt lgkmcnt(" #n ")" ::: "memory")
; template <class Epi, class Sched, bool ALIGN_EPI = true, bool SP2 = true>
; __device__ __forceinline__ void gemm_phase(PG8_LAS unsigned char* lds, const Gemm g, const Sched& S, const Epi& E, const int tid) {
;     ...
;             const bool last = (t == nt - 2);
;             const char* a1 = cA + (size_t)(t + 1) * kstep;
;             const char* a2 = last ? nA : cA + (size_t)(t + 2) * kstep; const char* b2 = last ? nB : cB + (size_t)(t + 2) * kstep;
;             const char* a3 = a2 + kstep; const char* b3 = b2 + kstep;
;             if (last && has_next) S.a_ready(nxt);
;             if constexpr (SP2) {
;             PG8_LDB(B0, 0, 0); PG8_LDB(B1, 0, 1); PG8_SCHED; PG8_LDA(At, 0, 0); PG8_STAGE(PG8_SA(1, 1), a1 + hstepA, voffA);
;             PG8_WAIT_V(8); PG8_WAIT_L(0); PG8_BAR; PG8_MMA(0, 0, At, B0); PG8_MMA(0, 1, At, B1); PG8_BAR; PG8_SCHED;
;             PG8_LDA(At, 0, 1); PG8_STAGE(PG8_SB(0, 0), b2, voffB); PG8_STAGE(PG8_SB(0, 1), b2 + hstepB, voffB); PG8_STAGE(PG8_SA(0, 0), a2, voffA);
;             PG8_WAIT_V(8); PG8_WAIT_L(0); PG8_BAR; PG8_MMA(1, 0, At, B0); PG8_MMA(1, 1, At, B1); PG8_BAR; PG8_SCHED;
.LBB0_381:
	s_add_u32 s25, s62, 0xfff80080
	s_addc_u32 s26, s63, -1
	s_add_i32 s27, 0, 0x10000
	s_cmp_eq_u32 s24, 28
	s_cselect_b32 s69, s18, s26
	s_cselect_b32 s68, s19, s25
	s_cselect_b32 s67, s20, s23
	s_cselect_b32 s66, s21, s22
	s_add_i32 s25, 0, 0x14000
	v_add_u32_e32 v158, s27, v163
	v_add_u32_e32 v165, s25, v163
	ds_read_b128 v[146:149], v158
	ds_read_b128 v[150:153], v158 offset:1024
	ds_read_b128 v[154:157], v158 offset:2048
	ds_read_b128 v[158:161], v158 offset:3072
	ds_read_b128 v[166:169], v165
	ds_read_b128 v[170:173], v165 offset:1024
	ds_read_b128 v[174:177], v165 offset:2048
	ds_read_b128 v[178:181], v165 offset:3072
	s_add_i32 m0, s82, 0xc000
	ds_read_b128 v[182:185], v164
	ds_read_b128 v[186:189], v164 offset:1024
	ds_read_b128 v[190:193], v164 offset:2048
	ds_read_b128 v[194:197], v164 offset:3072
	ds_read_b128 v[206:209], v164 offset:4096
	ds_read_b128 v[210:213], v164 offset:5120
	ds_read_b128 v[222:225], v164 offset:6144
	ds_read_b128 v[226:229], v164 offset:7168
	global_load_lds_dwordx4 v142, s[62:63]
	s_add_i32 m0, s82, 0xe000
	s_nop 0
	global_load_lds_dwordx4 v144, s[62:63]
	s_waitcnt vmcnt(8)
	s_waitcnt lgkmcnt(0)
	s_barrier
	s_setprio 1
	s_waitcnt lgkmcnt(0)
	v_mfma_f32_16x16x32_bf16 v[126:129], v[146:149], v[182:185], v[126:129]
	v_mfma_f32_16x16x32_bf16 v[122:125], v[154:157], v[182:185], v[122:125]
	v_mfma_f32_16x16x32_bf16 v[110:113], v[146:149], v[190:193], v[110:113]
	v_mfma_f32_16x16x32_bf16 v[106:109], v[154:157], v[190:193], v[106:109]
	v_mfma_f32_16x16x32_bf16 v[92:95], v[146:149], v[206:209], v[92:95]
	v_mfma_f32_16x16x32_bf16 v[88:91], v[154:157], v[206:209], v[88:91]
	v_mfma_f32_16x16x32_bf16 v[76:79], v[146:149], v[222:225], v[76:79]
	v_mfma_f32_16x16x32_bf16 v[72:75], v[154:157], v[222:225], v[72:75]
	v_mfma_f32_16x16x32_bf16 v[126:129], v[150:153], v[186:189], v[126:129]
	v_mfma_f32_16x16x32_bf16 v[122:125], v[158:161], v[186:189], v[122:125]
	v_mfma_f32_16x16x32_bf16 v[110:113], v[150:153], v[194:197], v[110:113]
	v_mfma_f32_16x16x32_bf16 v[106:109], v[158:161], v[194:197], v[106:109]
	v_mfma_f32_16x16x32_bf16 v[92:95], v[150:153], v[210:213], v[92:95]
	v_mfma_f32_16x16x32_bf16 v[88:91], v[158:161], v[210:213], v[88:91]
	v_mfma_f32_16x16x32_bf16 v[76:79], v[150:153], v[226:229], v[76:79]
	v_mfma_f32_16x16x32_bf16 v[72:75], v[158:161], v[226:229], v[72:75]
	s_setprio 0
	s_setprio 1
	v_mfma_f32_16x16x32_bf16 v[118:121], v[166:169], v[182:185], v[118:121]
	v_mfma_f32_16x16x32_bf16 v[114:117], v[174:177], v[182:185], v[114:117]
	v_mfma_f32_16x16x32_bf16 v[102:105], v[166:169], v[190:193], v[102:105]
	v_mfma_f32_16x16x32_bf16 v[98:101], v[174:177], v[190:193], v[98:101]
	v_mfma_f32_16x16x32_bf16 v[84:87], v[166:169], v[206:209], v[84:87]
	v_mfma_f32_16x16x32_bf16 v[80:83], v[174:177], v[206:209], v[80:83]
	v_mfma_f32_16x16x32_bf16 v[68:71], v[166:169], v[222:225], v[68:71]
	v_mfma_f32_16x16x32_bf16 v[64:67], v[174:177], v[222:225], v[64:67]
	v_mfma_f32_16x16x32_bf16 v[118:121], v[170:173], v[186:189], v[118:121]
	v_mfma_f32_16x16x32_bf16 v[114:117], v[178:181], v[186:189], v[114:117]
	v_mfma_f32_16x16x32_bf16 v[102:105], v[170:173], v[194:197], v[102:105]
	v_mfma_f32_16x16x32_bf16 v[98:101], v[178:181], v[194:197], v[98:101]
	v_mfma_f32_16x16x32_bf16 v[84:87], v[170:173], v[210:213], v[84:87]
	v_mfma_f32_16x16x32_bf16 v[80:83], v[178:181], v[210:213], v[80:83]
	v_mfma_f32_16x16x32_bf16 v[68:71], v[170:173], v[226:229], v[68:71]
	v_mfma_f32_16x16x32_bf16 v[64:67], v[178:181], v[226:229], v[64:67]
	s_setprio 0
	s_barrier
	s_add_i32 s26, s27, s73
	s_mov_b32 m0, s26
	ds_read_b128 v[182:185], v164 offset:16384
	ds_read_b128 v[186:189], v164 offset:17408
	ds_read_b128 v[190:193], v164 offset:18432
	ds_read_b128 v[194:197], v164 offset:19456
	ds_read_b128 v[206:209], v164 offset:20480
	ds_read_b128 v[210:213], v164 offset:21504
	ds_read_b128 v[222:225], v164 offset:22528
	ds_read_b128 v[226:229], v164 offset:23552
	global_load_lds_dwordx4 v132, s[66:67]
	s_add_i32 m0, s26, 0x2000
	s_add_u32 s26, s66, 0x80000
	s_addc_u32 s27, s67, 0
	s_add_i32 s25, s25, s73
	global_load_lds_dwordx4 v136, s[66:67]
	s_mov_b32 m0, s25
	s_nop 0
	global_load_lds_dwordx4 v132, s[26:27]
	s_add_i32 m0, s25, 0x2000
	s_nop 0
	global_load_lds_dwordx4 v136, s[26:27]
	s_mov_b32 m0, s82
	s_nop 0
	global_load_lds_dwordx4 v130, s[68:69]
	s_mov_b32 m0, s83
	s_nop 0
	global_load_lds_dwordx4 v134, s[68:69]
	s_waitcnt vmcnt(8)
	s_waitcnt lgkmcnt(0)
	s_barrier
	s_setprio 1
	s_waitcnt lgkmcnt(0)
	v_mfma_f32_16x16x32_bf16 v[60:63], v[146:149], v[182:185], v[60:63]
	v_mfma_f32_16x16x32_bf16 v[56:59], v[154:157], v[182:185], v[56:59]
	v_mfma_f32_16x16x32_bf16 v[44:47], v[146:149], v[190:193], v[44:47]
	v_mfma_f32_16x16x32_bf16 v[40:43], v[154:157], v[190:193], v[40:43]
	v_mfma_f32_16x16x32_bf16 v[28:31], v[146:149], v[206:209], v[28:31]
	v_mfma_f32_16x16x32_bf16 v[24:27], v[154:157], v[206:209], v[24:27]
	v_mfma_f32_16x16x32_bf16 v[12:15], v[146:149], v[222:225], v[12:15]
	v_mfma_f32_16x16x32_bf16 v[8:11], v[154:157], v[222:225], v[8:11]
	v_mfma_f32_16x16x32_bf16 v[60:63], v[150:153], v[186:189], v[60:63]
	v_mfma_f32_16x16x32_bf16 v[56:59], v[158:161], v[186:189], v[56:59]
	v_mfma_f32_16x16x32_bf16 v[44:47], v[150:153], v[194:197], v[44:47]
	v_mfma_f32_16x16x32_bf16 v[40:43], v[158:161], v[194:197], v[40:43]
	v_mfma_f32_16x16x32_bf16 v[28:31], v[150:153], v[210:213], v[28:31]
	v_mfma_f32_16x16x32_bf16 v[24:27], v[158:161], v[210:213], v[24:27]
	v_mfma_f32_16x16x32_bf16 v[12:15], v[150:153], v[226:229], v[12:15]
	v_mfma_f32_16x16x32_bf16 v[8:11], v[158:161], v[226:229], v[8:11]
	s_setprio 0
	s_setprio 1
	v_mfma_f32_16x16x32_bf16 v[52:55], v[166:169], v[182:185], v[52:55]
	v_mfma_f32_16x16x32_bf16 v[48:51], v[174:177], v[182:185], v[48:51]
	v_mfma_f32_16x16x32_bf16 v[36:39], v[166:169], v[190:193], v[36:39]
	v_mfma_f32_16x16x32_bf16 v[32:35], v[174:177], v[190:193], v[32:35]
	v_mfma_f32_16x16x32_bf16 v[20:23], v[166:169], v[206:209], v[20:23]
	v_mfma_f32_16x16x32_bf16 v[16:19], v[174:177], v[206:209], v[16:19]
	v_mfma_f32_16x16x32_bf16 v[4:7], v[166:169], v[222:225], v[4:7]
	v_mfma_f32_16x16x32_bf16 v[0:3], v[174:177], v[222:225], v[0:3]
	v_mfma_f32_16x16x32_bf16 v[52:55], v[170:173], v[186:189], v[52:55]
	v_mfma_f32_16x16x32_bf16 v[48:51], v[178:181], v[186:189], v[48:51]
	v_mfma_f32_16x16x32_bf16 v[36:39], v[170:173], v[194:197], v[36:39]
	v_mfma_f32_16x16x32_bf16 v[32:35], v[178:181], v[194:197], v[32:35]
	v_mfma_f32_16x16x32_bf16 v[20:23], v[170:173], v[210:213], v[20:23]
	v_mfma_f32_16x16x32_bf16 v[16:19], v[178:181], v[210:213], v[16:19]
	v_mfma_f32_16x16x32_bf16 v[4:7], v[170:173], v[226:229], v[4:7]
	v_mfma_f32_16x16x32_bf16 v[0:3], v[178:181], v[226:229], v[0:3]
	s_setprio 0
	s_barrier
; #define PG8_STAGE(bufoff, gbase, voff) do { _Pragma("unroll") for (int _i = 0; _i < 2; ++_i) \
;         __builtin_amdgcn_global_load_lds((const unsigned*)((const char*)(gbase) + (voff)[_i]), (PG8_LAS unsigned*)(lds + (bufoff) + ldsw + _i * 8192), 16, 0, 0); } while (0)
; #define PG8_LDA(dst, b, h) do { _Pragma("unroll") for (int m = 0; m < 4; ++m) _Pragma("unroll") for (int k = 0; k < 2; ++k) dst[m][k] = *(const PG8_LAS bf16x8*)(lds + PG8_SA(b, h) + aoff + m * 2048 + k * 1024); } while (0)
; #define PG8_LDB(dst, b, h) do { _Pragma("unroll") for (int n = 0; n < 2; ++n) _Pragma("unroll") for (int k = 0; k < 2; ++k) dst[n][k] = *(const PG8_LAS bf16x8*)(lds + PG8_SB(b, h) + boff + n * 2048 + k * 1024); } while (0)
; #define PG8_MMA(ai, bj, At, Bt) do { __builtin_amdgcn_s_setprio(1); _Pragma("unroll") for (int m = 0; m < 4; ++m) _Pragma("unroll") for (int n = 0; n < 2; ++n) _Pragma("unroll") for (int k = 0; k < 2; ++k) \
;         acc[ai][bj][m][n] = __builtin_amdgcn_mfma_f32_16x16x32_bf16(Bt[n][k], At[m][k], acc[ai][bj][m][n], 0, 0, 0); __builtin_amdgcn_s_setprio(0); } while (0)
; #define PG8_WAIT_V(n) asm volatile("s_waitcnt vmcnt(" #n ")" ::: "memory")
; #define PG8_WAIT_L(n) asm volatile("s_waitcnt lgkmcnt(" #n ")" ::: "memory")
; #define PG8_BAR __builtin_amdgcn_s_barrier()
; #define PG8_SCHED __builtin_amdgcn_sched_barrier(0)
; template <class Epi, class Sched, bool ALIGN_EPI = true, bool SP2 = true>
; __device__ __forceinline__ void gemm_phase(PG8_LAS unsigned char* lds, const Gemm g, const Sched& S, const Epi& E, const int tid) {
;     ...
;             PG8_LDB(B0, 1, 0); PG8_LDB(B1, 1, 1); PG8_SCHED; PG8_LDA(At, 1, 0); PG8_STAGE(PG8_SA(0, 1), a2 + hstepA, voffA);
;             PG8_WAIT_V(8); PG8_WAIT_L(0); PG8_BAR; PG8_MMA(0, 0, At, B0); PG8_MMA(0, 1, At, B1); PG8_BAR; PG8_SCHED;
;             PG8_LDA(At, 1, 1); PG8_STAGE(PG8_SB(1, 0), b3, voffB); PG8_STAGE(PG8_SB(1, 1), b3 + hstepB, voffB); PG8_STAGE(PG8_SA(1, 0), a3, voffA);
;             PG8_WAIT_V(8); PG8_WAIT_L(0); PG8_BAR; PG8_MMA(1, 0, At, B0); PG8_MMA(1, 1, At, B1); PG8_BAR; PG8_SCHED;
	s_add_i32 s25, 0, 0x18000
	s_add_i32 s28, 0, 0x1c000
	v_add_u32_e32 v158, s25, v163
	v_add_u32_e32 v165, s28, v163
	ds_read_b128 v[146:149], v158
	ds_read_b128 v[150:153], v158 offset:1024
	ds_read_b128 v[154:157], v158 offset:2048
	ds_read_b128 v[158:161], v158 offset:3072
	ds_read_b128 v[166:169], v165
	ds_read_b128 v[170:173], v165 offset:1024
	ds_read_b128 v[174:177], v165 offset:2048
	ds_read_b128 v[178:181], v165 offset:3072
	s_add_u32 s26, s68, 0x80000
	s_addc_u32 s27, s69, 0
	s_mov_b32 m0, s84
	ds_read_b128 v[182:185], v164 offset:32768
	ds_read_b128 v[186:189], v164 offset:33792
	ds_read_b128 v[190:193], v164 offset:34816
	ds_read_b128 v[194:197], v164 offset:35840
	ds_read_b128 v[206:209], v164 offset:36864
	ds_read_b128 v[210:213], v164 offset:37888
	ds_read_b128 v[222:225], v164 offset:38912
	ds_read_b128 v[226:229], v164 offset:39936
	global_load_lds_dwordx4 v130, s[26:27]
	s_mov_b32 m0, s85
	s_nop 0
	global_load_lds_dwordx4 v134, s[26:27]
	s_waitcnt vmcnt(8)
	s_waitcnt lgkmcnt(0)
	s_barrier
	s_setprio 1
	s_waitcnt lgkmcnt(0)
	v_mfma_f32_16x16x32_bf16 v[126:129], v[146:149], v[182:185], v[126:129]
	v_mfma_f32_16x16x32_bf16 v[122:125], v[154:157], v[182:185], v[122:125]
	v_mfma_f32_16x16x32_bf16 v[110:113], v[146:149], v[190:193], v[110:113]
	v_mfma_f32_16x16x32_bf16 v[106:109], v[154:157], v[190:193], v[106:109]
	v_mfma_f32_16x16x32_bf16 v[92:95], v[146:149], v[206:209], v[92:95]
	v_mfma_f32_16x16x32_bf16 v[88:91], v[154:157], v[206:209], v[88:91]
	v_mfma_f32_16x16x32_bf16 v[76:79], v[146:149], v[222:225], v[76:79]
	v_mfma_f32_16x16x32_bf16 v[72:75], v[154:157], v[222:225], v[72:75]
	v_mfma_f32_16x16x32_bf16 v[126:129], v[150:153], v[186:189], v[126:129]
	v_mfma_f32_16x16x32_bf16 v[122:125], v[158:161], v[186:189], v[122:125]
	v_mfma_f32_16x16x32_bf16 v[110:113], v[150:153], v[194:197], v[110:113]
	v_mfma_f32_16x16x32_bf16 v[106:109], v[158:161], v[194:197], v[106:109]
	v_mfma_f32_16x16x32_bf16 v[92:95], v[150:153], v[210:213], v[92:95]
	v_mfma_f32_16x16x32_bf16 v[88:91], v[158:161], v[210:213], v[88:91]
	v_mfma_f32_16x16x32_bf16 v[76:79], v[150:153], v[226:229], v[76:79]
	v_mfma_f32_16x16x32_bf16 v[72:75], v[158:161], v[226:229], v[72:75]
	s_setprio 0
	s_setprio 1
	v_mfma_f32_16x16x32_bf16 v[118:121], v[166:169], v[182:185], v[118:121]
	v_mfma_f32_16x16x32_bf16 v[114:117], v[174:177], v[182:185], v[114:117]
	v_mfma_f32_16x16x32_bf16 v[102:105], v[166:169], v[190:193], v[102:105]
	v_mfma_f32_16x16x32_bf16 v[98:101], v[174:177], v[190:193], v[98:101]
	v_mfma_f32_16x16x32_bf16 v[84:87], v[166:169], v[206:209], v[84:87]
	v_mfma_f32_16x16x32_bf16 v[80:83], v[174:177], v[206:209], v[80:83]
	v_mfma_f32_16x16x32_bf16 v[68:71], v[166:169], v[222:225], v[68:71]
	v_mfma_f32_16x16x32_bf16 v[64:67], v[174:177], v[222:225], v[64:67]
	v_mfma_f32_16x16x32_bf16 v[118:121], v[170:173], v[186:189], v[118:121]
	v_mfma_f32_16x16x32_bf16 v[114:117], v[178:181], v[186:189], v[114:117]
	v_mfma_f32_16x16x32_bf16 v[102:105], v[170:173], v[194:197], v[102:105]
	v_mfma_f32_16x16x32_bf16 v[98:101], v[178:181], v[194:197], v[98:101]
	v_mfma_f32_16x16x32_bf16 v[84:87], v[170:173], v[210:213], v[84:87]
	v_mfma_f32_16x16x32_bf16 v[80:83], v[178:181], v[210:213], v[80:83]
	v_mfma_f32_16x16x32_bf16 v[68:71], v[170:173], v[226:229], v[68:71]
	v_mfma_f32_16x16x32_bf16 v[64:67], v[178:181], v[226:229], v[64:67]
	s_setprio 0
	s_barrier
	s_add_i32 s25, s25, s73
	s_add_u32 s4, s66, 0x80
	s_addc_u32 s5, s67, 0
	s_mov_b32 m0, s25
	ds_read_b128 v[182:185], v164 offset:49152
	ds_read_b128 v[186:189], v164 offset:50176
	ds_read_b128 v[190:193], v164 offset:51200
	ds_read_b128 v[194:197], v164 offset:52224
	ds_read_b128 v[206:209], v164 offset:53248
	ds_read_b128 v[210:213], v164 offset:54272
	ds_read_b128 v[222:225], v164 offset:55296
	ds_read_b128 v[226:229], v164 offset:56320
	global_load_lds_dwordx4 v132, s[4:5]
	s_add_i32 m0, s25, 0x2000
	s_add_u32 s26, s66, 0x80080
	s_addc_u32 s27, s67, 0
	s_add_i32 s25, s28, s73
	global_load_lds_dwordx4 v136, s[4:5]
	s_mov_b32 m0, s25
	s_nop 0
	global_load_lds_dwordx4 v132, s[26:27]
	s_add_i32 m0, s25, 0x2000
	s_nop 0
	global_load_lds_dwordx4 v136, s[26:27]
	s_add_u32 s4, s68, 0x80
	s_addc_u32 s5, s69, 0
	s_mov_b32 m0, s88
	s_nop 0
	global_load_lds_dwordx4 v130, s[4:5]
	s_mov_b32 m0, s89
	s_nop 0
	global_load_lds_dwordx4 v134, s[4:5]
	s_waitcnt vmcnt(8)
	s_waitcnt lgkmcnt(0)
	s_barrier
	s_setprio 1
	s_waitcnt lgkmcnt(0)
	v_mfma_f32_16x16x32_bf16 v[60:63], v[146:149], v[182:185], v[60:63]
	v_mfma_f32_16x16x32_bf16 v[56:59], v[154:157], v[182:185], v[56:59]
	v_mfma_f32_16x16x32_bf16 v[44:47], v[146:149], v[190:193], v[44:47]
	v_mfma_f32_16x16x32_bf16 v[40:43], v[154:157], v[190:193], v[40:43]
	v_mfma_f32_16x16x32_bf16 v[28:31], v[146:149], v[206:209], v[28:31]
	v_mfma_f32_16x16x32_bf16 v[24:27], v[154:157], v[206:209], v[24:27]
	v_mfma_f32_16x16x32_bf16 v[12:15], v[146:149], v[222:225], v[12:15]
	v_mfma_f32_16x16x32_bf16 v[8:11], v[154:157], v[222:225], v[8:11]
	v_mfma_f32_16x16x32_bf16 v[60:63], v[150:153], v[186:189], v[60:63]
	v_mfma_f32_16x16x32_bf16 v[56:59], v[158:161], v[186:189], v[56:59]
	v_mfma_f32_16x16x32_bf16 v[44:47], v[150:153], v[194:197], v[44:47]
	v_mfma_f32_16x16x32_bf16 v[40:43], v[158:161], v[194:197], v[40:43]
	v_mfma_f32_16x16x32_bf16 v[28:31], v[150:153], v[210:213], v[28:31]
	v_mfma_f32_16x16x32_bf16 v[24:27], v[158:161], v[210:213], v[24:27]
	v_mfma_f32_16x16x32_bf16 v[12:15], v[150:153], v[226:229], v[12:15]
	v_mfma_f32_16x16x32_bf16 v[8:11], v[158:161], v[226:229], v[8:11]
	s_setprio 0
	s_setprio 1
	v_mfma_f32_16x16x32_bf16 v[52:55], v[166:169], v[182:185], v[52:55]
	v_mfma_f32_16x16x32_bf16 v[48:51], v[174:177], v[182:185], v[48:51]
	v_mfma_f32_16x16x32_bf16 v[36:39], v[166:169], v[190:193], v[36:39]
	v_mfma_f32_16x16x32_bf16 v[32:35], v[174:177], v[190:193], v[32:35]
	v_mfma_f32_16x16x32_bf16 v[20:23], v[166:169], v[206:209], v[20:23]
	v_mfma_f32_16x16x32_bf16 v[16:19], v[174:177], v[206:209], v[16:19]
	v_mfma_f32_16x16x32_bf16 v[4:7], v[166:169], v[222:225], v[4:7]
	v_mfma_f32_16x16x32_bf16 v[0:3], v[174:177], v[222:225], v[0:3]
	v_mfma_f32_16x16x32_bf16 v[52:55], v[170:173], v[186:189], v[52:55]
	v_mfma_f32_16x16x32_bf16 v[48:51], v[178:181], v[186:189], v[48:51]
	v_mfma_f32_16x16x32_bf16 v[36:39], v[170:173], v[194:197], v[36:39]
	v_mfma_f32_16x16x32_bf16 v[32:35], v[178:181], v[194:197], v[32:35]
	v_mfma_f32_16x16x32_bf16 v[20:23], v[170:173], v[210:213], v[20:23]
	v_mfma_f32_16x16x32_bf16 v[16:19], v[178:181], v[210:213], v[16:19]
	v_mfma_f32_16x16x32_bf16 v[4:7], v[170:173], v[226:229], v[4:7]
	v_mfma_f32_16x16x32_bf16 v[0:3], v[178:181], v[226:229], v[0:3]
	s_setprio 0
	s_barrier
	s_add_i32 s24, s24, 2
	s_add_u32 s62, s62, 0x100
	s_addc_u32 s63, s63, 0
	s_add_u32 s22, s22, 0x100
	s_addc_u32 s23, s23, 0
	s_cmp_gt_u32 s24, 29
	s_cbranch_scc0 .LBB0_381
	s_mov_b64 s[4:5], 0x80
	s_and_b64 vcc, exec, s[52:53]
	s_cbranch_vccz .LBB0_384
	s_barrier

; #define PG8_STAGE(bufoff, gbase, voff) do { _Pragma("unroll") for (int _i = 0; _i < 2; ++_i) \
;         __builtin_amdgcn_global_load_lds((const unsigned*)((const char*)(gbase) + (voff)[_i]), (PG8_LAS unsigned*)(lds + (bufoff) + ldsw + _i * 8192), 16, 0, 0); } while (0)
; #define PG8_LDA(dst, b, h) do { _Pragma("unroll") for (int m = 0; m < 4; ++m) _Pragma("unroll") for (int k = 0; k < 2; ++k) dst[m][k] = *(const PG8_LAS bf16x8*)(lds + PG8_SA(b, h) + aoff + m * 2048 + k * 1024); } while (0)
; #define PG8_LDB(dst, b, h) do { _Pragma("unroll") for (int n = 0; n < 2; ++n) _Pragma("unroll") for (int k = 0; k < 2; ++k) dst[n][k] = *(const PG8_LAS bf16x8*)(lds + PG8_SB(b, h) + boff + n * 2048 + k * 1024); } while (0)
; #define PG8_MMA(ai, bj, At, Bt) do { __builtin_amdgcn_s_setprio(1); _Pragma("unroll") for (int m = 0; m < 4; ++m) _Pragma("unroll") for (int n = 0; n < 2; ++n) _Pragma("unroll") for (int k = 0; k < 2; ++k) \
;         acc[ai][bj][m][n] = __builtin_amdgcn_mfma_f32_16x16x32_bf16(Bt[n][k], At[m][k], acc[ai][bj][m][n], 0, 0, 0); __builtin_amdgcn_s_setprio(0); } while (0)
; #define PG8_WAIT_V(n) asm volatile("s_waitcnt vmcnt(" #n ")" ::: "memory")
; #define PG8_WAIT_L(n) asm volatile("s_waitcnt lgkmcnt(" #n ")" ::: "memory")
; template <class Epi, class Sched, bool ALIGN_EPI = true, bool SP2 = true>
; __device__ __forceinline__ void gemm_phase(PG8_LAS unsigned char* lds, const Gemm g, const Sched& S, const Epi& E, const int tid) {
;     ...
;             const bool last = (t == nt - 2);
;             const char* a1 = cA + (size_t)(t + 1) * kstep;
;             const char* a2 = last ? nA : cA + (size_t)(t + 2) * kstep; const char* b2 = last ? nB : cB + (size_t)(t + 2) * kstep;
;             const char* a3 = a2 + kstep; const char* b3 = b2 + kstep;
;             if (last && has_next) S.a_ready(nxt);
;             if constexpr (SP2) {
;             PG8_LDB(B0, 0, 0); PG8_LDB(B1, 0, 1); PG8_SCHED; PG8_LDA(At, 0, 0); PG8_STAGE(PG8_SA(1, 1), a1 + hstepA, voffA);
;             PG8_WAIT_V(8); PG8_WAIT_L(0); PG8_BAR; PG8_MMA(0, 0, At, B0); PG8_MMA(0, 1, At, B1); PG8_BAR; PG8_SCHED;
;             PG8_LDA(At, 0, 1); PG8_STAGE(PG8_SB(0, 0), b2, voffB); PG8_STAGE(PG8_SB(0, 1), b2 + hstepB, voffB); PG8_STAGE(PG8_SA(0, 0), a2, voffA);
;             PG8_WAIT_V(8); PG8_WAIT_L(0); PG8_BAR; PG8_MMA(1, 0, At, B0); PG8_MMA(1, 1, At, B1); PG8_BAR; PG8_SCHED;
.LBB0_700:
	s_add_i32 s29, s28, 2
	s_add_u32 s40, s42, 0x100
	s_addc_u32 s41, s43, 0
	s_add_i32 s48, 0, 0x10000
	s_cmp_eq_u32 s25, s28
	s_cselect_b32 s47, s71, s41
	s_cselect_b32 s46, s70, s40
	s_cselect_b32 s45, s73, s27
	s_cselect_b32 s44, s72, s26
	s_add_i32 s28, 0, 0x14000
	v_add_u32_e32 v162, s48, v152
	v_add_u32_e32 v178, s28, v152
	ds_read_b128 v[144:147], v162
	ds_read_b128 v[154:157], v162 offset:1024
	ds_read_b128 v[158:161], v162 offset:2048
	ds_read_b128 v[162:165], v162 offset:3072
	ds_read_b128 v[166:169], v178
	ds_read_b128 v[170:173], v178 offset:1024
	ds_read_b128 v[174:177], v178 offset:2048
	ds_read_b128 v[178:181], v178 offset:3072
	s_add_i32 m0, s89, 0xc000
	ds_read_b128 v[182:185], v153
	ds_read_b128 v[186:189], v153 offset:1024
	ds_read_b128 v[190:193], v153 offset:2048
	ds_read_b128 v[194:197], v153 offset:3072
	ds_read_b128 v[206:209], v153 offset:4096
	ds_read_b128 v[210:213], v153 offset:5120
	ds_read_b128 v[222:225], v153 offset:6144
	ds_read_b128 v[226:229], v153 offset:7168
	global_load_lds_dwordx4 v140, s[42:43]
	s_add_i32 m0, s89, 0xe000
	s_nop 0
	global_load_lds_dwordx4 v142, s[42:43]
	s_waitcnt vmcnt(8)
	s_waitcnt lgkmcnt(0)
	s_barrier
	s_setprio 1
	s_waitcnt lgkmcnt(0)
	v_mfma_f32_16x16x32_bf16 v[126:129], v[144:147], v[182:185], v[126:129]
	v_mfma_f32_16x16x32_bf16 v[122:125], v[158:161], v[182:185], v[122:125]
	v_mfma_f32_16x16x32_bf16 v[110:113], v[144:147], v[190:193], v[110:113]
	v_mfma_f32_16x16x32_bf16 v[106:109], v[158:161], v[190:193], v[106:109]
	v_mfma_f32_16x16x32_bf16 v[92:95], v[144:147], v[206:209], v[92:95]
	v_mfma_f32_16x16x32_bf16 v[88:91], v[158:161], v[206:209], v[88:91]
	v_mfma_f32_16x16x32_bf16 v[76:79], v[144:147], v[222:225], v[76:79]
	v_mfma_f32_16x16x32_bf16 v[72:75], v[158:161], v[222:225], v[72:75]
	v_mfma_f32_16x16x32_bf16 v[126:129], v[154:157], v[186:189], v[126:129]
	v_mfma_f32_16x16x32_bf16 v[122:125], v[162:165], v[186:189], v[122:125]
	v_mfma_f32_16x16x32_bf16 v[110:113], v[154:157], v[194:197], v[110:113]
	v_mfma_f32_16x16x32_bf16 v[106:109], v[162:165], v[194:197], v[106:109]
	v_mfma_f32_16x16x32_bf16 v[92:95], v[154:157], v[210:213], v[92:95]
	v_mfma_f32_16x16x32_bf16 v[88:91], v[162:165], v[210:213], v[88:91]
	v_mfma_f32_16x16x32_bf16 v[76:79], v[154:157], v[226:229], v[76:79]
	v_mfma_f32_16x16x32_bf16 v[72:75], v[162:165], v[226:229], v[72:75]
	s_setprio 0
	s_setprio 1
	v_mfma_f32_16x16x32_bf16 v[118:121], v[166:169], v[182:185], v[118:121]
	v_mfma_f32_16x16x32_bf16 v[114:117], v[174:177], v[182:185], v[114:117]
	v_mfma_f32_16x16x32_bf16 v[102:105], v[166:169], v[190:193], v[102:105]
	v_mfma_f32_16x16x32_bf16 v[98:101], v[174:177], v[190:193], v[98:101]
	v_mfma_f32_16x16x32_bf16 v[84:87], v[166:169], v[206:209], v[84:87]
	v_mfma_f32_16x16x32_bf16 v[80:83], v[174:177], v[206:209], v[80:83]
	v_mfma_f32_16x16x32_bf16 v[68:71], v[166:169], v[222:225], v[68:71]
	v_mfma_f32_16x16x32_bf16 v[64:67], v[174:177], v[222:225], v[64:67]
	v_mfma_f32_16x16x32_bf16 v[118:121], v[170:173], v[186:189], v[118:121]
	v_mfma_f32_16x16x32_bf16 v[114:117], v[178:181], v[186:189], v[114:117]
	v_mfma_f32_16x16x32_bf16 v[102:105], v[170:173], v[194:197], v[102:105]
	v_mfma_f32_16x16x32_bf16 v[98:101], v[178:181], v[194:197], v[98:101]
	v_mfma_f32_16x16x32_bf16 v[84:87], v[170:173], v[210:213], v[84:87]
	v_mfma_f32_16x16x32_bf16 v[80:83], v[178:181], v[210:213], v[80:83]
	v_mfma_f32_16x16x32_bf16 v[68:71], v[170:173], v[226:229], v[68:71]
	v_mfma_f32_16x16x32_bf16 v[64:67], v[178:181], v[226:229], v[64:67]
	s_setprio 0
	s_barrier
	s_add_i32 s42, s48, s88
	s_mov_b32 m0, s42
	ds_read_b128 v[182:185], v153 offset:16384
	ds_read_b128 v[186:189], v153 offset:17408
	ds_read_b128 v[190:193], v153 offset:18432
	ds_read_b128 v[194:197], v153 offset:19456
	ds_read_b128 v[206:209], v153 offset:20480
	ds_read_b128 v[210:213], v153 offset:21504
	ds_read_b128 v[222:225], v153 offset:22528
	ds_read_b128 v[226:229], v153 offset:23552
	global_load_lds_dwordx4 v132, s[44:45]
	s_add_i32 m0, s42, 0x2000
	s_add_u32 s42, s44, 0x28000
	s_addc_u32 s43, s45, 0
	s_add_i32 s28, s28, s88
	global_load_lds_dwordx4 v136, s[44:45]
	s_mov_b32 m0, s28
	s_nop 0
	global_load_lds_dwordx4 v132, s[42:43]
	s_add_i32 m0, s28, 0x2000
	s_nop 0
	global_load_lds_dwordx4 v136, s[42:43]
	s_mov_b32 m0, s89
	s_nop 0
	global_load_lds_dwordx4 v130, s[46:47]
	s_mov_b32 m0, s90
	s_nop 0
	global_load_lds_dwordx4 v134, s[46:47]
	s_waitcnt vmcnt(8)
	s_waitcnt lgkmcnt(0)
	s_barrier
	s_setprio 1
	s_waitcnt lgkmcnt(0)
	v_mfma_f32_16x16x32_bf16 v[60:63], v[144:147], v[182:185], v[60:63]
	v_mfma_f32_16x16x32_bf16 v[56:59], v[158:161], v[182:185], v[56:59]
	v_mfma_f32_16x16x32_bf16 v[44:47], v[144:147], v[190:193], v[44:47]
	v_mfma_f32_16x16x32_bf16 v[40:43], v[158:161], v[190:193], v[40:43]
	v_mfma_f32_16x16x32_bf16 v[28:31], v[144:147], v[206:209], v[28:31]
	v_mfma_f32_16x16x32_bf16 v[24:27], v[158:161], v[206:209], v[24:27]
	v_mfma_f32_16x16x32_bf16 v[12:15], v[144:147], v[222:225], v[12:15]
	v_mfma_f32_16x16x32_bf16 v[8:11], v[158:161], v[222:225], v[8:11]
	v_mfma_f32_16x16x32_bf16 v[60:63], v[154:157], v[186:189], v[60:63]
	v_mfma_f32_16x16x32_bf16 v[56:59], v[162:165], v[186:189], v[56:59]
	v_mfma_f32_16x16x32_bf16 v[44:47], v[154:157], v[194:197], v[44:47]
	v_mfma_f32_16x16x32_bf16 v[40:43], v[162:165], v[194:197], v[40:43]
	v_mfma_f32_16x16x32_bf16 v[28:31], v[154:157], v[210:213], v[28:31]
	v_mfma_f32_16x16x32_bf16 v[24:27], v[162:165], v[210:213], v[24:27]
	v_mfma_f32_16x16x32_bf16 v[12:15], v[154:157], v[226:229], v[12:15]
	v_mfma_f32_16x16x32_bf16 v[8:11], v[162:165], v[226:229], v[8:11]
	s_setprio 0
	s_setprio 1
	v_mfma_f32_16x16x32_bf16 v[52:55], v[166:169], v[182:185], v[52:55]
	v_mfma_f32_16x16x32_bf16 v[48:51], v[174:177], v[182:185], v[48:51]
	v_mfma_f32_16x16x32_bf16 v[36:39], v[166:169], v[190:193], v[36:39]
	v_mfma_f32_16x16x32_bf16 v[32:35], v[174:177], v[190:193], v[32:35]
	v_mfma_f32_16x16x32_bf16 v[20:23], v[166:169], v[206:209], v[20:23]
	v_mfma_f32_16x16x32_bf16 v[16:19], v[174:177], v[206:209], v[16:19]
	v_mfma_f32_16x16x32_bf16 v[4:7], v[166:169], v[222:225], v[4:7]
	v_mfma_f32_16x16x32_bf16 v[0:3], v[174:177], v[222:225], v[0:3]
	v_mfma_f32_16x16x32_bf16 v[52:55], v[170:173], v[186:189], v[52:55]
	v_mfma_f32_16x16x32_bf16 v[48:51], v[178:181], v[186:189], v[48:51]
	v_mfma_f32_16x16x32_bf16 v[36:39], v[170:173], v[194:197], v[36:39]
	v_mfma_f32_16x16x32_bf16 v[32:35], v[178:181], v[194:197], v[32:35]
	v_mfma_f32_16x16x32_bf16 v[20:23], v[170:173], v[210:213], v[20:23]
	v_mfma_f32_16x16x32_bf16 v[16:19], v[178:181], v[210:213], v[16:19]
	v_mfma_f32_16x16x32_bf16 v[4:7], v[170:173], v[226:229], v[4:7]
	v_mfma_f32_16x16x32_bf16 v[0:3], v[178:181], v[226:229], v[0:3]
	s_setprio 0
	s_barrier
; #define PG8_STAGE(bufoff, gbase, voff) do { _Pragma("unroll") for (int _i = 0; _i < 2; ++_i) \
;         __builtin_amdgcn_global_load_lds((const unsigned*)((const char*)(gbase) + (voff)[_i]), (PG8_LAS unsigned*)(lds + (bufoff) + ldsw + _i * 8192), 16, 0, 0); } while (0)
; #define PG8_LDA(dst, b, h) do { _Pragma("unroll") for (int m = 0; m < 4; ++m) _Pragma("unroll") for (int k = 0; k < 2; ++k) dst[m][k] = *(const PG8_LAS bf16x8*)(lds + PG8_SA(b, h) + aoff + m * 2048 + k * 1024); } while (0)
; #define PG8_LDB(dst, b, h) do { _Pragma("unroll") for (int n = 0; n < 2; ++n) _Pragma("unroll") for (int k = 0; k < 2; ++k) dst[n][k] = *(const PG8_LAS bf16x8*)(lds + PG8_SB(b, h) + boff + n * 2048 + k * 1024); } while (0)
; #define PG8_MMA(ai, bj, At, Bt) do { __builtin_amdgcn_s_setprio(1); _Pragma("unroll") for (int m = 0; m < 4; ++m) _Pragma("unroll") for (int n = 0; n < 2; ++n) _Pragma("unroll") for (int k = 0; k < 2; ++k) \
;         acc[ai][bj][m][n] = __builtin_amdgcn_mfma_f32_16x16x32_bf16(Bt[n][k], At[m][k], acc[ai][bj][m][n], 0, 0, 0); __builtin_amdgcn_s_setprio(0); } while (0)
; #define PG8_WAIT_V(n) asm volatile("s_waitcnt vmcnt(" #n ")" ::: "memory")
; #define PG8_WAIT_L(n) asm volatile("s_waitcnt lgkmcnt(" #n ")" ::: "memory")
; #define PG8_BAR __builtin_amdgcn_s_barrier()
; #define PG8_SCHED __builtin_amdgcn_sched_barrier(0)
; template <class Epi, class Sched, bool ALIGN_EPI = true, bool SP2 = true>
; __device__ __forceinline__ void gemm_phase(PG8_LAS unsigned char* lds, const Gemm g, const Sched& S, const Epi& E, const int tid) {
;     ...
;             PG8_LDB(B0, 1, 0); PG8_LDB(B1, 1, 1); PG8_SCHED; PG8_LDA(At, 1, 0); PG8_STAGE(PG8_SA(0, 1), a2 + hstepA, voffA);
;             PG8_WAIT_V(8); PG8_WAIT_L(0); PG8_BAR; PG8_MMA(0, 0, At, B0); PG8_MMA(0, 1, At, B1); PG8_BAR; PG8_SCHED;
;             PG8_LDA(At, 1, 1); PG8_STAGE(PG8_SB(1, 0), b3, voffB); PG8_STAGE(PG8_SB(1, 1), b3 + hstepB, voffB); PG8_STAGE(PG8_SA(1, 0), a3, voffA);
;             PG8_WAIT_V(8); PG8_WAIT_L(0); PG8_BAR; PG8_MMA(1, 0, At, B0); PG8_MMA(1, 1, At, B1); PG8_BAR; PG8_SCHED;
	s_add_i32 s28, 0, 0x18000
	s_add_i32 s48, 0, 0x1c000
	v_add_u32_e32 v162, s28, v152
	v_add_u32_e32 v178, s48, v152
	ds_read_b128 v[144:147], v162
	ds_read_b128 v[154:157], v162 offset:1024
	ds_read_b128 v[158:161], v162 offset:2048
	ds_read_b128 v[162:165], v162 offset:3072
	ds_read_b128 v[166:169], v178
	ds_read_b128 v[170:173], v178 offset:1024
	ds_read_b128 v[174:177], v178 offset:2048
	ds_read_b128 v[178:181], v178 offset:3072
	s_add_u32 s42, s46, 0x150000
	s_addc_u32 s43, s47, 0
	s_mov_b32 m0, s91
	ds_read_b128 v[182:185], v153 offset:32768
	ds_read_b128 v[186:189], v153 offset:33792
	ds_read_b128 v[190:193], v153 offset:34816
	ds_read_b128 v[194:197], v153 offset:35840
	ds_read_b128 v[206:209], v153 offset:36864
	ds_read_b128 v[210:213], v153 offset:37888
	ds_read_b128 v[222:225], v153 offset:38912
	ds_read_b128 v[226:229], v153 offset:39936
	global_load_lds_dwordx4 v130, s[42:43]
	s_mov_b32 m0, s80
	s_nop 0
	global_load_lds_dwordx4 v134, s[42:43]
	s_waitcnt vmcnt(8)
	s_waitcnt lgkmcnt(0)
	s_barrier
	s_setprio 1
	s_waitcnt lgkmcnt(0)
	v_mfma_f32_16x16x32_bf16 v[126:129], v[144:147], v[182:185], v[126:129]
	v_mfma_f32_16x16x32_bf16 v[122:125], v[158:161], v[182:185], v[122:125]
	v_mfma_f32_16x16x32_bf16 v[110:113], v[144:147], v[190:193], v[110:113]
	v_mfma_f32_16x16x32_bf16 v[106:109], v[158:161], v[190:193], v[106:109]
	v_mfma_f32_16x16x32_bf16 v[92:95], v[144:147], v[206:209], v[92:95]
	v_mfma_f32_16x16x32_bf16 v[88:91], v[158:161], v[206:209], v[88:91]
	v_mfma_f32_16x16x32_bf16 v[76:79], v[144:147], v[222:225], v[76:79]
	v_mfma_f32_16x16x32_bf16 v[72:75], v[158:161], v[222:225], v[72:75]
	v_mfma_f32_16x16x32_bf16 v[126:129], v[154:157], v[186:189], v[126:129]
	v_mfma_f32_16x16x32_bf16 v[122:125], v[162:165], v[186:189], v[122:125]
	v_mfma_f32_16x16x32_bf16 v[110:113], v[154:157], v[194:197], v[110:113]
	v_mfma_f32_16x16x32_bf16 v[106:109], v[162:165], v[194:197], v[106:109]
	v_mfma_f32_16x16x32_bf16 v[92:95], v[154:157], v[210:213], v[92:95]
	v_mfma_f32_16x16x32_bf16 v[88:91], v[162:165], v[210:213], v[88:91]
	v_mfma_f32_16x16x32_bf16 v[76:79], v[154:157], v[226:229], v[76:79]
	v_mfma_f32_16x16x32_bf16 v[72:75], v[162:165], v[226:229], v[72:75]
	s_setprio 0
	s_setprio 1
	v_mfma_f32_16x16x32_bf16 v[118:121], v[166:169], v[182:185], v[118:121]
	v_mfma_f32_16x16x32_bf16 v[114:117], v[174:177], v[182:185], v[114:117]
	v_mfma_f32_16x16x32_bf16 v[102:105], v[166:169], v[190:193], v[102:105]
	v_mfma_f32_16x16x32_bf16 v[98:101], v[174:177], v[190:193], v[98:101]
	v_mfma_f32_16x16x32_bf16 v[84:87], v[166:169], v[206:209], v[84:87]
	v_mfma_f32_16x16x32_bf16 v[80:83], v[174:177], v[206:209], v[80:83]
	v_mfma_f32_16x16x32_bf16 v[68:71], v[166:169], v[222:225], v[68:71]
	v_mfma_f32_16x16x32_bf16 v[64:67], v[174:177], v[222:225], v[64:67]
	v_mfma_f32_16x16x32_bf16 v[118:121], v[170:173], v[186:189], v[118:121]
	v_mfma_f32_16x16x32_bf16 v[114:117], v[178:181], v[186:189], v[114:117]
	v_mfma_f32_16x16x32_bf16 v[102:105], v[170:173], v[194:197], v[102:105]
	v_mfma_f32_16x16x32_bf16 v[98:101], v[178:181], v[194:197], v[98:101]
	v_mfma_f32_16x16x32_bf16 v[84:87], v[170:173], v[210:213], v[84:87]
	v_mfma_f32_16x16x32_bf16 v[80:83], v[178:181], v[210:213], v[80:83]
	v_mfma_f32_16x16x32_bf16 v[68:71], v[170:173], v[226:229], v[68:71]
	v_mfma_f32_16x16x32_bf16 v[64:67], v[178:181], v[226:229], v[64:67]
	s_setprio 0
	s_barrier
	s_add_i32 s28, s28, s88
	s_add_u32 s4, s44, 0x80
	s_addc_u32 s5, s45, 0
	s_mov_b32 m0, s28
	ds_read_b128 v[182:185], v153 offset:49152
	ds_read_b128 v[186:189], v153 offset:50176
	ds_read_b128 v[190:193], v153 offset:51200
	ds_read_b128 v[194:197], v153 offset:52224
	ds_read_b128 v[206:209], v153 offset:53248
	ds_read_b128 v[210:213], v153 offset:54272
	ds_read_b128 v[222:225], v153 offset:55296
	ds_read_b128 v[226:229], v153 offset:56320
	global_load_lds_dwordx4 v132, s[4:5]
	s_add_i32 m0, s28, 0x2000
	s_add_u32 s42, s44, 0x28080
	s_addc_u32 s43, s45, 0
	s_add_i32 s28, s48, s88
	global_load_lds_dwordx4 v136, s[4:5]
	s_mov_b32 m0, s28
	s_nop 0
	global_load_lds_dwordx4 v132, s[42:43]
	s_add_i32 m0, s28, 0x2000
	s_nop 0
	global_load_lds_dwordx4 v136, s[42:43]
	s_add_u32 s4, s46, 0x80
	s_addc_u32 s5, s47, 0
	s_mov_b32 m0, s56
	s_nop 0
	global_load_lds_dwordx4 v130, s[4:5]
	s_mov_b32 m0, s57
	s_nop 0
	global_load_lds_dwordx4 v134, s[4:5]
	s_waitcnt vmcnt(8)
	s_waitcnt lgkmcnt(0)
	s_barrier
	s_setprio 1
	s_waitcnt lgkmcnt(0)
	v_mfma_f32_16x16x32_bf16 v[60:63], v[144:147], v[182:185], v[60:63]
	v_mfma_f32_16x16x32_bf16 v[56:59], v[158:161], v[182:185], v[56:59]
	v_mfma_f32_16x16x32_bf16 v[44:47], v[144:147], v[190:193], v[44:47]
	v_mfma_f32_16x16x32_bf16 v[40:43], v[158:161], v[190:193], v[40:43]
	v_mfma_f32_16x16x32_bf16 v[28:31], v[144:147], v[206:209], v[28:31]
	v_mfma_f32_16x16x32_bf16 v[24:27], v[158:161], v[206:209], v[24:27]
	v_mfma_f32_16x16x32_bf16 v[12:15], v[144:147], v[222:225], v[12:15]
	v_mfma_f32_16x16x32_bf16 v[8:11], v[158:161], v[222:225], v[8:11]
	v_mfma_f32_16x16x32_bf16 v[60:63], v[154:157], v[186:189], v[60:63]
	v_mfma_f32_16x16x32_bf16 v[56:59], v[162:165], v[186:189], v[56:59]
	v_mfma_f32_16x16x32_bf16 v[44:47], v[154:157], v[194:197], v[44:47]
	v_mfma_f32_16x16x32_bf16 v[40:43], v[162:165], v[194:197], v[40:43]
	v_mfma_f32_16x16x32_bf16 v[28:31], v[154:157], v[210:213], v[28:31]
	v_mfma_f32_16x16x32_bf16 v[24:27], v[162:165], v[210:213], v[24:27]
	v_mfma_f32_16x16x32_bf16 v[12:15], v[154:157], v[226:229], v[12:15]
	v_mfma_f32_16x16x32_bf16 v[8:11], v[162:165], v[226:229], v[8:11]
	s_setprio 0
	s_setprio 1
	v_mfma_f32_16x16x32_bf16 v[52:55], v[166:169], v[182:185], v[52:55]
	v_mfma_f32_16x16x32_bf16 v[48:51], v[174:177], v[182:185], v[48:51]
	v_mfma_f32_16x16x32_bf16 v[36:39], v[166:169], v[190:193], v[36:39]
	v_mfma_f32_16x16x32_bf16 v[32:35], v[174:177], v[190:193], v[32:35]
	v_mfma_f32_16x16x32_bf16 v[20:23], v[166:169], v[206:209], v[20:23]
	v_mfma_f32_16x16x32_bf16 v[16:19], v[174:177], v[206:209], v[16:19]
	v_mfma_f32_16x16x32_bf16 v[4:7], v[166:169], v[222:225], v[4:7]
	v_mfma_f32_16x16x32_bf16 v[0:3], v[174:177], v[222:225], v[0:3]
	v_mfma_f32_16x16x32_bf16 v[52:55], v[170:173], v[186:189], v[52:55]
	v_mfma_f32_16x16x32_bf16 v[48:51], v[178:181], v[186:189], v[48:51]
	v_mfma_f32_16x16x32_bf16 v[36:39], v[170:173], v[194:197], v[36:39]
	v_mfma_f32_16x16x32_bf16 v[32:35], v[178:181], v[194:197], v[32:35]
	v_mfma_f32_16x16x32_bf16 v[20:23], v[170:173], v[210:213], v[20:23]
	v_mfma_f32_16x16x32_bf16 v[16:19], v[178:181], v[210:213], v[16:19]
	v_mfma_f32_16x16x32_bf16 v[4:7], v[170:173], v[226:229], v[4:7]
	v_mfma_f32_16x16x32_bf16 v[0:3], v[178:181], v[226:229], v[0:3]
	s_setprio 0
	s_barrier
	s_add_u32 s26, s26, 0x100
	s_addc_u32 s27, s27, 0
	s_cmp_ge_i32 s29, s24
	s_mov_b64 s[42:43], s[40:41]
	s_mov_b32 s28, s29
	s_cbranch_scc0 .LBB0_700
	s_mov_b64 s[4:5], 0x80
	s_and_b64 vcc, exec, s[64:65]
	s_cbranch_vccz .LBB0_703
	s_barrier

; #define PG8_STAGE(bufoff, gbase, voff) do { _Pragma("unroll") for (int _i = 0; _i < 2; ++_i) \
;         __builtin_amdgcn_global_load_lds((const unsigned*)((const char*)(gbase) + (voff)[_i]), (PG8_LAS unsigned*)(lds + (bufoff) + ldsw + _i * 8192), 16, 0, 0); } while (0)
; #define PG8_LDA(dst, b, h) do { _Pragma("unroll") for (int m = 0; m < 4; ++m) _Pragma("unroll") for (int k = 0; k < 2; ++k) dst[m][k] = *(const PG8_LAS bf16x8*)(lds + PG8_SA(b, h) + aoff + m * 2048 + k * 1024); } while (0)
; #define PG8_LDB(dst, b, h) do { _Pragma("unroll") for (int n = 0; n < 2; ++n) _Pragma("unroll") for (int k = 0; k < 2; ++k) dst[n][k] = *(const PG8_LAS bf16x8*)(lds + PG8_SB(b, h) + boff + n * 2048 + k * 1024); } while (0)
; #define PG8_MMA(ai, bj, At, Bt) do { __builtin_amdgcn_s_setprio(1); _Pragma("unroll") for (int m = 0; m < 4; ++m) _Pragma("unroll") for (int n = 0; n < 2; ++n) _Pragma("unroll") for (int k = 0; k < 2; ++k) \
;         acc[ai][bj][m][n] = __builtin_amdgcn_mfma_f32_16x16x32_bf16(Bt[n][k], At[m][k], acc[ai][bj][m][n], 0, 0, 0); __builtin_amdgcn_s_setprio(0); } while (0)
; #define PG8_WAIT_V(n) asm volatile("s_waitcnt vmcnt(" #n ")" ::: "memory")
; #define PG8_WAIT_L(n) asm volatile("s_waitcnt lgkmcnt(" #n ")" ::: "memory")
; template <class Epi, class Sched, bool ALIGN_EPI = true, bool SP2 = true>
; __device__ __forceinline__ void gemm_phase(PG8_LAS unsigned char* lds, const Gemm g, const Sched& S, const Epi& E, const int tid) {
;     ...
;             const bool last = (t == nt - 2);
;             const char* a1 = cA + (size_t)(t + 1) * kstep;
;             const char* a2 = last ? nA : cA + (size_t)(t + 2) * kstep; const char* b2 = last ? nB : cB + (size_t)(t + 2) * kstep;
;             const char* a3 = a2 + kstep; const char* b3 = b2 + kstep;
;             if (last && has_next) S.a_ready(nxt);
;             if constexpr (SP2) {
;             PG8_LDB(B0, 0, 0); PG8_LDB(B1, 0, 1); PG8_SCHED; PG8_LDA(At, 0, 0); PG8_STAGE(PG8_SA(1, 1), a1 + hstepA, voffA);
;             PG8_WAIT_V(8); PG8_WAIT_L(0); PG8_BAR; PG8_MMA(0, 0, At, B0); PG8_MMA(0, 1, At, B1); PG8_BAR; PG8_SCHED;
;             PG8_LDA(At, 0, 1); PG8_STAGE(PG8_SB(0, 0), b2, voffB); PG8_STAGE(PG8_SB(0, 1), b2 + hstepB, voffB); PG8_STAGE(PG8_SA(0, 0), a2, voffA);
;             PG8_WAIT_V(8); PG8_WAIT_L(0); PG8_BAR; PG8_MMA(1, 0, At, B0); PG8_MMA(1, 1, At, B1); PG8_BAR; PG8_SCHED;
.LBB0_1077:
	s_add_i32 s63, s82, 2
	s_add_u32 s83, s80, 0xfff80080
	s_addc_u32 s84, s81, -1
	s_add_i32 vcc_lo, 0, 0x10000
	s_cmp_eq_u32 s29, s82
	s_cselect_b32 s85, s67, s84
	s_cselect_b32 s84, s66, s83
	v_add_u32_e32 v96, vcc_lo, v141
	s_cselect_b32 s83, s69, s61
	s_cselect_b32 s82, s68, s59
	s_add_i32 s30, 0, 0x14000
	ds_read_b128 v[146:149], v96
	ds_read_b128 v[150:153], v96 offset:1024
	ds_read_b128 v[154:157], v96 offset:2048
	ds_read_b128 v[158:161], v96 offset:3072
	v_add_u32_e32 v96, s30, v141
	ds_read_b128 v[162:165], v96
	ds_read_b128 v[166:169], v96 offset:1024
	ds_read_b128 v[170:173], v96 offset:2048
	ds_read_b128 v[174:177], v96 offset:3072
	s_add_i32 m0, s25, 0xc000
	ds_read_b128 v[178:181], v145
	ds_read_b128 v[182:185], v145 offset:1024
	ds_read_b128 v[186:189], v145 offset:2048
	ds_read_b128 v[190:193], v145 offset:3072
	ds_read_b128 v[194:197], v145 offset:4096
	ds_read_b128 v[200:203], v145 offset:5120
	ds_read_b128 v[206:209], v145 offset:6144
	ds_read_b128 v[210:213], v145 offset:7168
	global_load_lds_dwordx4 v136, s[80:81]
	s_add_i32 m0, s25, 0xe000
	s_nop 0
	global_load_lds_dwordx4 v138, s[80:81]
	s_waitcnt vmcnt(8)
	s_waitcnt lgkmcnt(0)
	s_barrier
	s_setprio 1
	s_waitcnt lgkmcnt(0)
	v_mfma_f32_16x16x32_bf16 v[92:95], v[146:149], v[178:181], v[92:95]
	v_mfma_f32_16x16x32_bf16 v[130:133], v[154:157], v[178:181], v[130:133]
	v_mfma_f32_16x16x32_bf16 v[126:129], v[146:149], v[186:189], v[126:129]
	v_mfma_f32_16x16x32_bf16 v[122:125], v[154:157], v[186:189], v[122:125]
	v_mfma_f32_16x16x32_bf16 v[118:121], v[146:149], v[194:197], v[118:121]
	v_mfma_f32_16x16x32_bf16 v[110:113], v[154:157], v[194:197], v[110:113]
	v_mfma_f32_16x16x32_bf16 v[76:79], v[146:149], v[206:209], v[76:79]
	v_mfma_f32_16x16x32_bf16 v[72:75], v[154:157], v[206:209], v[72:75]
	v_mfma_f32_16x16x32_bf16 v[92:95], v[150:153], v[182:185], v[92:95]
	v_mfma_f32_16x16x32_bf16 v[130:133], v[158:161], v[182:185], v[130:133]
	v_mfma_f32_16x16x32_bf16 v[126:129], v[150:153], v[190:193], v[126:129]
	v_mfma_f32_16x16x32_bf16 v[122:125], v[158:161], v[190:193], v[122:125]
	v_mfma_f32_16x16x32_bf16 v[118:121], v[150:153], v[200:203], v[118:121]
	v_mfma_f32_16x16x32_bf16 v[110:113], v[158:161], v[200:203], v[110:113]
	v_mfma_f32_16x16x32_bf16 v[76:79], v[150:153], v[210:213], v[76:79]
	v_mfma_f32_16x16x32_bf16 v[72:75], v[158:161], v[210:213], v[72:75]
	s_setprio 0
	s_setprio 1
	v_mfma_f32_16x16x32_bf16 v[88:91], v[162:165], v[178:181], v[88:91]
	v_mfma_f32_16x16x32_bf16 v[84:87], v[170:173], v[178:181], v[84:87]
	v_mfma_f32_16x16x32_bf16 v[114:117], v[162:165], v[186:189], v[114:117]
	v_mfma_f32_16x16x32_bf16 v[106:109], v[170:173], v[186:189], v[106:109]
	v_mfma_f32_16x16x32_bf16 v[102:105], v[162:165], v[194:197], v[102:105]
	v_mfma_f32_16x16x32_bf16 v[80:83], v[170:173], v[194:197], v[80:83]
	v_mfma_f32_16x16x32_bf16 v[68:71], v[162:165], v[206:209], v[68:71]
	v_mfma_f32_16x16x32_bf16 v[64:67], v[170:173], v[206:209], v[64:67]
	v_mfma_f32_16x16x32_bf16 v[88:91], v[166:169], v[182:185], v[88:91]
	v_mfma_f32_16x16x32_bf16 v[84:87], v[174:177], v[182:185], v[84:87]
	v_mfma_f32_16x16x32_bf16 v[114:117], v[166:169], v[190:193], v[114:117]
	v_mfma_f32_16x16x32_bf16 v[106:109], v[174:177], v[190:193], v[106:109]
	v_mfma_f32_16x16x32_bf16 v[102:105], v[166:169], v[200:203], v[102:105]
	v_mfma_f32_16x16x32_bf16 v[80:83], v[174:177], v[200:203], v[80:83]
	v_mfma_f32_16x16x32_bf16 v[68:71], v[166:169], v[210:213], v[68:71]
	v_mfma_f32_16x16x32_bf16 v[64:67], v[174:177], v[210:213], v[64:67]
	s_setprio 0
	s_barrier
	s_add_i32 s31, vcc_lo, s24
	s_mov_b32 m0, s31
	ds_read_b128 v[178:181], v145 offset:16384
	ds_read_b128 v[182:185], v145 offset:17408
	ds_read_b128 v[186:189], v145 offset:18432
	ds_read_b128 v[190:193], v145 offset:19456
	ds_read_b128 v[194:197], v145 offset:20480
	ds_read_b128 v[200:203], v145 offset:21504
	ds_read_b128 v[206:209], v145 offset:22528
	ds_read_b128 v[210:213], v145 offset:23552
	global_load_lds_dwordx4 v100, s[82:83]
	s_add_i32 m0, s31, 0x2000
	s_add_u32 vcc_lo, s82, 0x80000
	s_addc_u32 vcc_hi, s83, 0
	s_add_i32 s30, s30, s24
	global_load_lds_dwordx4 v134, s[82:83]
	s_mov_b32 m0, s30
	s_nop 0
	global_load_lds_dwordx4 v100, vcc
	s_add_i32 m0, s30, 0x2000
	s_nop 0
	global_load_lds_dwordx4 v134, vcc
	s_mov_b32 m0, s25
	s_nop 0
	global_load_lds_dwordx4 v100, s[84:85]
	s_mov_b32 m0, s49
	s_nop 0
	global_load_lds_dwordx4 v134, s[84:85]
	s_waitcnt vmcnt(8)
	s_waitcnt lgkmcnt(0)
	s_barrier
	s_setprio 1
	s_waitcnt lgkmcnt(0)
	v_mfma_f32_16x16x32_bf16 v[56:59], v[146:149], v[178:181], v[56:59]
	v_mfma_f32_16x16x32_bf16 v[60:63], v[154:157], v[178:181], v[60:63]
	v_mfma_f32_16x16x32_bf16 v[44:47], v[146:149], v[186:189], v[44:47]
	v_mfma_f32_16x16x32_bf16 v[40:43], v[154:157], v[186:189], v[40:43]
	v_mfma_f32_16x16x32_bf16 v[28:31], v[146:149], v[194:197], v[28:31]
	v_mfma_f32_16x16x32_bf16 v[24:27], v[154:157], v[194:197], v[24:27]
	v_mfma_f32_16x16x32_bf16 v[12:15], v[146:149], v[206:209], v[12:15]
	v_mfma_f32_16x16x32_bf16 v[8:11], v[154:157], v[206:209], v[8:11]
	v_mfma_f32_16x16x32_bf16 v[56:59], v[150:153], v[182:185], v[56:59]
	v_mfma_f32_16x16x32_bf16 v[60:63], v[158:161], v[182:185], v[60:63]
	v_mfma_f32_16x16x32_bf16 v[44:47], v[150:153], v[190:193], v[44:47]
	v_mfma_f32_16x16x32_bf16 v[40:43], v[158:161], v[190:193], v[40:43]
	v_mfma_f32_16x16x32_bf16 v[28:31], v[150:153], v[200:203], v[28:31]
	v_mfma_f32_16x16x32_bf16 v[24:27], v[158:161], v[200:203], v[24:27]
	v_mfma_f32_16x16x32_bf16 v[12:15], v[150:153], v[210:213], v[12:15]
	v_mfma_f32_16x16x32_bf16 v[8:11], v[158:161], v[210:213], v[8:11]
	s_setprio 0
	s_setprio 1
	v_mfma_f32_16x16x32_bf16 v[52:55], v[162:165], v[178:181], v[52:55]
	v_mfma_f32_16x16x32_bf16 v[48:51], v[170:173], v[178:181], v[48:51]
	v_mfma_f32_16x16x32_bf16 v[36:39], v[162:165], v[186:189], v[36:39]
	v_mfma_f32_16x16x32_bf16 v[32:35], v[170:173], v[186:189], v[32:35]
	v_mfma_f32_16x16x32_bf16 v[20:23], v[162:165], v[194:197], v[20:23]
	v_mfma_f32_16x16x32_bf16 v[16:19], v[170:173], v[194:197], v[16:19]
	v_mfma_f32_16x16x32_bf16 v[4:7], v[162:165], v[206:209], v[4:7]
	v_mfma_f32_16x16x32_bf16 v[0:3], v[170:173], v[206:209], v[0:3]
	v_mfma_f32_16x16x32_bf16 v[52:55], v[166:169], v[182:185], v[52:55]
	v_mfma_f32_16x16x32_bf16 v[48:51], v[174:177], v[182:185], v[48:51]
	v_mfma_f32_16x16x32_bf16 v[36:39], v[166:169], v[190:193], v[36:39]
	v_mfma_f32_16x16x32_bf16 v[32:35], v[174:177], v[190:193], v[32:35]
	v_mfma_f32_16x16x32_bf16 v[20:23], v[166:169], v[200:203], v[20:23]
	v_mfma_f32_16x16x32_bf16 v[16:19], v[174:177], v[200:203], v[16:19]
	v_mfma_f32_16x16x32_bf16 v[4:7], v[166:169], v[210:213], v[4:7]
	v_mfma_f32_16x16x32_bf16 v[0:3], v[174:177], v[210:213], v[0:3]
	s_setprio 0
	s_barrier
; #define PG8_STAGE(bufoff, gbase, voff) do { _Pragma("unroll") for (int _i = 0; _i < 2; ++_i) \
;         __builtin_amdgcn_global_load_lds((const unsigned*)((const char*)(gbase) + (voff)[_i]), (PG8_LAS unsigned*)(lds + (bufoff) + ldsw + _i * 8192), 16, 0, 0); } while (0)
; #define PG8_LDA(dst, b, h) do { _Pragma("unroll") for (int m = 0; m < 4; ++m) _Pragma("unroll") for (int k = 0; k < 2; ++k) dst[m][k] = *(const PG8_LAS bf16x8*)(lds + PG8_SA(b, h) + aoff + m * 2048 + k * 1024); } while (0)
; #define PG8_LDB(dst, b, h) do { _Pragma("unroll") for (int n = 0; n < 2; ++n) _Pragma("unroll") for (int k = 0; k < 2; ++k) dst[n][k] = *(const PG8_LAS bf16x8*)(lds + PG8_SB(b, h) + boff + n * 2048 + k * 1024); } while (0)
; #define PG8_MMA(ai, bj, At, Bt) do { __builtin_amdgcn_s_setprio(1); _Pragma("unroll") for (int m = 0; m < 4; ++m) _Pragma("unroll") for (int n = 0; n < 2; ++n) _Pragma("unroll") for (int k = 0; k < 2; ++k) \
;         acc[ai][bj][m][n] = __builtin_amdgcn_mfma_f32_16x16x32_bf16(Bt[n][k], At[m][k], acc[ai][bj][m][n], 0, 0, 0); __builtin_amdgcn_s_setprio(0); } while (0)
; #define PG8_WAIT_V(n) asm volatile("s_waitcnt vmcnt(" #n ")" ::: "memory")
; #define PG8_WAIT_L(n) asm volatile("s_waitcnt lgkmcnt(" #n ")" ::: "memory")
; #define PG8_BAR __builtin_amdgcn_s_barrier()
; #define PG8_SCHED __builtin_amdgcn_sched_barrier(0)
; template <class Epi, class Sched, bool ALIGN_EPI = true, bool SP2 = true>
; __device__ __forceinline__ void gemm_phase(PG8_LAS unsigned char* lds, const Gemm g, const Sched& S, const Epi& E, const int tid) {
;     ...
;             PG8_LDB(B0, 1, 0); PG8_LDB(B1, 1, 1); PG8_SCHED; PG8_LDA(At, 1, 0); PG8_STAGE(PG8_SA(0, 1), a2 + hstepA, voffA);
;             PG8_WAIT_V(8); PG8_WAIT_L(0); PG8_BAR; PG8_MMA(0, 0, At, B0); PG8_MMA(0, 1, At, B1); PG8_BAR; PG8_SCHED;
;             PG8_LDA(At, 1, 1); PG8_STAGE(PG8_SB(1, 0), b3, voffB); PG8_STAGE(PG8_SB(1, 1), b3 + hstepB, voffB); PG8_STAGE(PG8_SA(1, 0), a3, voffA);
;             PG8_WAIT_V(8); PG8_WAIT_L(0); PG8_BAR; PG8_MMA(1, 0, At, B0); PG8_MMA(1, 1, At, B1); PG8_BAR; PG8_SCHED;
	s_add_i32 s30, 0, 0x18000
	v_add_u32_e32 v96, s30, v141
	s_add_i32 s31, 0, 0x1c000
	ds_read_b128 v[146:149], v96
	ds_read_b128 v[150:153], v96 offset:1024
	ds_read_b128 v[154:157], v96 offset:2048
	ds_read_b128 v[158:161], v96 offset:3072
	v_add_u32_e32 v96, s31, v141
	ds_read_b128 v[162:165], v96
	ds_read_b128 v[166:169], v96 offset:1024
	ds_read_b128 v[170:173], v96 offset:2048
	ds_read_b128 v[174:177], v96 offset:3072
	s_add_u32 s84, s84, 0x80000
	s_addc_u32 s85, s85, 0
	s_mov_b32 m0, s51
	ds_read_b128 v[178:181], v145 offset:32768
	ds_read_b128 v[182:185], v145 offset:33792
	ds_read_b128 v[186:189], v145 offset:34816
	ds_read_b128 v[190:193], v145 offset:35840
	ds_read_b128 v[194:197], v145 offset:36864
	ds_read_b128 v[200:203], v145 offset:37888
	ds_read_b128 v[206:209], v145 offset:38912
	ds_read_b128 v[210:213], v145 offset:39936
	global_load_lds_dwordx4 v100, s[84:85]
	s_mov_b32 m0, s76
	s_nop 0
	global_load_lds_dwordx4 v134, s[84:85]
	s_waitcnt vmcnt(8)
	s_waitcnt lgkmcnt(0)
	s_barrier
	s_setprio 1
	s_waitcnt lgkmcnt(0)
	v_mfma_f32_16x16x32_bf16 v[92:95], v[146:149], v[178:181], v[92:95]
	v_mfma_f32_16x16x32_bf16 v[130:133], v[154:157], v[178:181], v[130:133]
	v_mfma_f32_16x16x32_bf16 v[126:129], v[146:149], v[186:189], v[126:129]
	v_mfma_f32_16x16x32_bf16 v[122:125], v[154:157], v[186:189], v[122:125]
	v_mfma_f32_16x16x32_bf16 v[118:121], v[146:149], v[194:197], v[118:121]
	v_mfma_f32_16x16x32_bf16 v[110:113], v[154:157], v[194:197], v[110:113]
	v_mfma_f32_16x16x32_bf16 v[76:79], v[146:149], v[206:209], v[76:79]
	v_mfma_f32_16x16x32_bf16 v[72:75], v[154:157], v[206:209], v[72:75]
	v_mfma_f32_16x16x32_bf16 v[92:95], v[150:153], v[182:185], v[92:95]
	v_mfma_f32_16x16x32_bf16 v[130:133], v[158:161], v[182:185], v[130:133]
	v_mfma_f32_16x16x32_bf16 v[126:129], v[150:153], v[190:193], v[126:129]
	v_mfma_f32_16x16x32_bf16 v[122:125], v[158:161], v[190:193], v[122:125]
	v_mfma_f32_16x16x32_bf16 v[118:121], v[150:153], v[200:203], v[118:121]
	v_mfma_f32_16x16x32_bf16 v[110:113], v[158:161], v[200:203], v[110:113]
	v_mfma_f32_16x16x32_bf16 v[76:79], v[150:153], v[210:213], v[76:79]
	v_mfma_f32_16x16x32_bf16 v[72:75], v[158:161], v[210:213], v[72:75]
	s_setprio 0
	s_setprio 1
	v_mfma_f32_16x16x32_bf16 v[88:91], v[162:165], v[178:181], v[88:91]
	v_mfma_f32_16x16x32_bf16 v[84:87], v[170:173], v[178:181], v[84:87]
	v_mfma_f32_16x16x32_bf16 v[114:117], v[162:165], v[186:189], v[114:117]
	v_mfma_f32_16x16x32_bf16 v[106:109], v[170:173], v[186:189], v[106:109]
	v_mfma_f32_16x16x32_bf16 v[102:105], v[162:165], v[194:197], v[102:105]
	v_mfma_f32_16x16x32_bf16 v[80:83], v[170:173], v[194:197], v[80:83]
	v_mfma_f32_16x16x32_bf16 v[68:71], v[162:165], v[206:209], v[68:71]
	v_mfma_f32_16x16x32_bf16 v[64:67], v[170:173], v[206:209], v[64:67]
	v_mfma_f32_16x16x32_bf16 v[88:91], v[166:169], v[182:185], v[88:91]
	v_mfma_f32_16x16x32_bf16 v[84:87], v[174:177], v[182:185], v[84:87]
	v_mfma_f32_16x16x32_bf16 v[114:117], v[166:169], v[190:193], v[114:117]
	v_mfma_f32_16x16x32_bf16 v[106:109], v[174:177], v[190:193], v[106:109]
	v_mfma_f32_16x16x32_bf16 v[102:105], v[166:169], v[200:203], v[102:105]
	v_mfma_f32_16x16x32_bf16 v[80:83], v[174:177], v[200:203], v[80:83]
	v_mfma_f32_16x16x32_bf16 v[68:71], v[166:169], v[210:213], v[68:71]
	v_mfma_f32_16x16x32_bf16 v[64:67], v[174:177], v[210:213], v[64:67]
	s_setprio 0
	s_barrier
	s_add_i32 s30, s30, s24
	s_add_u32 s4, s82, 0x80
	s_addc_u32 s5, s83, 0
	s_mov_b32 m0, s30
	ds_read_b128 v[178:181], v145 offset:49152
	ds_read_b128 v[182:185], v145 offset:50176
	ds_read_b128 v[186:189], v145 offset:51200
	ds_read_b128 v[190:193], v145 offset:52224
	ds_read_b128 v[194:197], v145 offset:53248
	ds_read_b128 v[200:203], v145 offset:54272
	ds_read_b128 v[206:209], v145 offset:55296
	ds_read_b128 v[210:213], v145 offset:56320
	global_load_lds_dwordx4 v100, s[4:5]
	s_add_i32 m0, s30, 0x2000
	s_add_u32 s82, s82, 0x80080
	s_addc_u32 s83, s83, 0
	s_add_i32 s30, s31, s24
	global_load_lds_dwordx4 v134, s[4:5]
	s_mov_b32 m0, s30
	s_nop 0
	global_load_lds_dwordx4 v100, s[82:83]
	s_add_i32 m0, s30, 0x2000
	s_nop 0
	global_load_lds_dwordx4 v134, s[82:83]
	s_add_u32 s4, s84, 0xfff80080
	s_addc_u32 s5, s85, -1
	s_mov_b32 m0, s90
	s_nop 0
	global_load_lds_dwordx4 v100, s[4:5]
	s_mov_b32 m0, s91
	s_nop 0
	global_load_lds_dwordx4 v134, s[4:5]
	s_waitcnt vmcnt(8)
	s_waitcnt lgkmcnt(0)
	s_barrier
	s_setprio 1
	s_waitcnt lgkmcnt(0)
	v_mfma_f32_16x16x32_bf16 v[56:59], v[146:149], v[178:181], v[56:59]
	v_mfma_f32_16x16x32_bf16 v[60:63], v[154:157], v[178:181], v[60:63]
	v_mfma_f32_16x16x32_bf16 v[44:47], v[146:149], v[186:189], v[44:47]
	v_mfma_f32_16x16x32_bf16 v[40:43], v[154:157], v[186:189], v[40:43]
	v_mfma_f32_16x16x32_bf16 v[28:31], v[146:149], v[194:197], v[28:31]
	v_mfma_f32_16x16x32_bf16 v[24:27], v[154:157], v[194:197], v[24:27]
	v_mfma_f32_16x16x32_bf16 v[12:15], v[146:149], v[206:209], v[12:15]
	v_mfma_f32_16x16x32_bf16 v[8:11], v[154:157], v[206:209], v[8:11]
	v_mfma_f32_16x16x32_bf16 v[56:59], v[150:153], v[182:185], v[56:59]
	v_mfma_f32_16x16x32_bf16 v[60:63], v[158:161], v[182:185], v[60:63]
	v_mfma_f32_16x16x32_bf16 v[44:47], v[150:153], v[190:193], v[44:47]
	v_mfma_f32_16x16x32_bf16 v[40:43], v[158:161], v[190:193], v[40:43]
	v_mfma_f32_16x16x32_bf16 v[28:31], v[150:153], v[200:203], v[28:31]
	v_mfma_f32_16x16x32_bf16 v[24:27], v[158:161], v[200:203], v[24:27]
	v_mfma_f32_16x16x32_bf16 v[12:15], v[150:153], v[210:213], v[12:15]
	v_mfma_f32_16x16x32_bf16 v[8:11], v[158:161], v[210:213], v[8:11]
	s_setprio 0
	s_setprio 1
	v_mfma_f32_16x16x32_bf16 v[52:55], v[162:165], v[178:181], v[52:55]
	v_mfma_f32_16x16x32_bf16 v[48:51], v[170:173], v[178:181], v[48:51]
	v_mfma_f32_16x16x32_bf16 v[36:39], v[162:165], v[186:189], v[36:39]
	v_mfma_f32_16x16x32_bf16 v[32:35], v[170:173], v[186:189], v[32:35]
	v_mfma_f32_16x16x32_bf16 v[20:23], v[162:165], v[194:197], v[20:23]
	v_mfma_f32_16x16x32_bf16 v[16:19], v[170:173], v[194:197], v[16:19]
	v_mfma_f32_16x16x32_bf16 v[4:7], v[162:165], v[206:209], v[4:7]
	v_mfma_f32_16x16x32_bf16 v[0:3], v[170:173], v[206:209], v[0:3]
	v_mfma_f32_16x16x32_bf16 v[52:55], v[166:169], v[182:185], v[52:55]
	v_mfma_f32_16x16x32_bf16 v[48:51], v[174:177], v[182:185], v[48:51]
	v_mfma_f32_16x16x32_bf16 v[36:39], v[166:169], v[190:193], v[36:39]
	v_mfma_f32_16x16x32_bf16 v[32:35], v[174:177], v[190:193], v[32:35]
	v_mfma_f32_16x16x32_bf16 v[20:23], v[166:169], v[200:203], v[20:23]
	v_mfma_f32_16x16x32_bf16 v[16:19], v[174:177], v[200:203], v[16:19]
	v_mfma_f32_16x16x32_bf16 v[4:7], v[166:169], v[210:213], v[4:7]
	v_mfma_f32_16x16x32_bf16 v[0:3], v[174:177], v[210:213], v[0:3]
	s_setprio 0
	s_barrier
	s_add_u32 s80, s80, 0x100
	s_addc_u32 s81, s81, 0
	s_add_u32 s59, s59, 0x100
	s_addc_u32 s61, s61, 0
	s_cmp_ge_i32 s63, s57
	s_mov_b32 s82, s63
	s_cbranch_scc0 .LBB0_1077
	s_mov_b64 s[4:5], 0x80

; #define PG8_STAGE(bufoff, gbase, voff) do { _Pragma("unroll") for (int _i = 0; _i < 2; ++_i) \
;         __builtin_amdgcn_global_load_lds((const unsigned*)((const char*)(gbase) + (voff)[_i]), (PG8_LAS unsigned*)(lds + (bufoff) + ldsw + _i * 8192), 16, 0, 0); } while (0)
; #define PG8_LDA(dst, b, h) do { _Pragma("unroll") for (int m = 0; m < 4; ++m) _Pragma("unroll") for (int k = 0; k < 2; ++k) dst[m][k] = *(const PG8_LAS bf16x8*)(lds + PG8_SA(b, h) + aoff + m * 2048 + k * 1024); } while (0)
; #define PG8_LDB(dst, b, h) do { _Pragma("unroll") for (int n = 0; n < 2; ++n) _Pragma("unroll") for (int k = 0; k < 2; ++k) dst[n][k] = *(const PG8_LAS bf16x8*)(lds + PG8_SB(b, h) + boff + n * 2048 + k * 1024); } while (0)
; #define PG8_MMA(ai, bj, At, Bt) do { __builtin_amdgcn_s_setprio(1); _Pragma("unroll") for (int m = 0; m < 4; ++m) _Pragma("unroll") for (int n = 0; n < 2; ++n) _Pragma("unroll") for (int k = 0; k < 2; ++k) \
;         acc[ai][bj][m][n] = __builtin_amdgcn_mfma_f32_16x16x32_bf16(Bt[n][k], At[m][k], acc[ai][bj][m][n], 0, 0, 0); __builtin_amdgcn_s_setprio(0); } while (0)
; #define PG8_WAIT_V(n) asm volatile("s_waitcnt vmcnt(" #n ")" ::: "memory")
; #define PG8_WAIT_L(n) asm volatile("s_waitcnt lgkmcnt(" #n ")" ::: "memory")
; template <class Epi, class Sched, bool ALIGN_EPI = true, bool SP2 = true>
; __device__ __forceinline__ void gemm_phase(PG8_LAS unsigned char* lds, const Gemm g, const Sched& S, const Epi& E, const int tid) {
;     ...
;             const bool last = (t == nt - 2);
;             const char* a1 = cA + (size_t)(t + 1) * kstep;
;             const char* a2 = last ? nA : cA + (size_t)(t + 2) * kstep; const char* b2 = last ? nB : cB + (size_t)(t + 2) * kstep;
;             const char* a3 = a2 + kstep; const char* b3 = b2 + kstep;
;             if (last && has_next) S.a_ready(nxt);
;             if constexpr (SP2) {
;             PG8_LDB(B0, 0, 0); PG8_LDB(B1, 0, 1); PG8_SCHED; PG8_LDA(At, 0, 0); PG8_STAGE(PG8_SA(1, 1), a1 + hstepA, voffA);
;             PG8_WAIT_V(8); PG8_WAIT_L(0); PG8_BAR; PG8_MMA(0, 0, At, B0); PG8_MMA(0, 1, At, B1); PG8_BAR; PG8_SCHED;
;             PG8_LDA(At, 0, 1); PG8_STAGE(PG8_SB(0, 0), b2, voffB); PG8_STAGE(PG8_SB(0, 1), b2 + hstepB, voffB); PG8_STAGE(PG8_SA(0, 0), a2, voffA);
;             PG8_WAIT_V(8); PG8_WAIT_L(0); PG8_BAR; PG8_MMA(1, 0, At, B0); PG8_MMA(1, 1, At, B1); PG8_BAR; PG8_SCHED;
.LBB0_1319:
	s_add_u32 s28, s62, 0xfff80080
	s_addc_u32 s29, s63, -1
	s_add_i32 s30, 0, 0x10000
	s_cmp_eq_u32 s52, 28
	s_cselect_b32 s67, s24, s29
	s_cselect_b32 s66, s25, s28
	v_add_u32_e32 v145, s30, v142
	s_cselect_b32 s65, s26, s51
	s_cselect_b32 s64, s27, s49
	s_add_i32 s31, 0, 0x14000
	ds_read_b128 v[146:149], v145
	ds_read_b128 v[150:153], v145 offset:1024
	ds_read_b128 v[154:157], v145 offset:2048
	ds_read_b128 v[158:161], v145 offset:3072
	v_add_u32_e32 v145, s31, v142
	ds_read_b128 v[162:165], v145
	ds_read_b128 v[166:169], v145 offset:1024
	ds_read_b128 v[170:173], v145 offset:2048
	ds_read_b128 v[174:177], v145 offset:3072
	s_add_i32 m0, s22, 0xc000
	ds_read_b128 v[178:181], v144
	ds_read_b128 v[182:185], v144 offset:1024
	ds_read_b128 v[186:189], v144 offset:2048
	ds_read_b128 v[190:193], v144 offset:3072
	ds_read_b128 v[194:197], v144 offset:4096
	ds_read_b128 v[200:203], v144 offset:5120
	ds_read_b128 v[206:209], v144 offset:6144
	ds_read_b128 v[210:213], v144 offset:7168
	global_load_lds_dwordx4 v138, s[62:63]
	s_add_i32 m0, s22, 0xe000
	s_nop 0
	global_load_lds_dwordx4 v140, s[62:63]
	s_waitcnt vmcnt(8)
	s_waitcnt lgkmcnt(0)
	s_barrier
	s_setprio 1
	s_waitcnt lgkmcnt(0)
	v_mfma_f32_16x16x32_bf16 v[126:129], v[146:149], v[178:181], v[126:129]
	v_mfma_f32_16x16x32_bf16 v[118:121], v[154:157], v[178:181], v[118:121]
	v_mfma_f32_16x16x32_bf16 v[110:113], v[146:149], v[186:189], v[110:113]
	v_mfma_f32_16x16x32_bf16 v[102:105], v[154:157], v[186:189], v[102:105]
	v_mfma_f32_16x16x32_bf16 v[92:95], v[146:149], v[194:197], v[92:95]
	v_mfma_f32_16x16x32_bf16 v[84:87], v[154:157], v[194:197], v[84:87]
	v_mfma_f32_16x16x32_bf16 v[76:79], v[146:149], v[206:209], v[76:79]
	v_mfma_f32_16x16x32_bf16 v[68:71], v[154:157], v[206:209], v[68:71]
	v_mfma_f32_16x16x32_bf16 v[126:129], v[150:153], v[182:185], v[126:129]
	v_mfma_f32_16x16x32_bf16 v[118:121], v[158:161], v[182:185], v[118:121]
	v_mfma_f32_16x16x32_bf16 v[110:113], v[150:153], v[190:193], v[110:113]
	v_mfma_f32_16x16x32_bf16 v[102:105], v[158:161], v[190:193], v[102:105]
	v_mfma_f32_16x16x32_bf16 v[92:95], v[150:153], v[200:203], v[92:95]
	v_mfma_f32_16x16x32_bf16 v[84:87], v[158:161], v[200:203], v[84:87]
	v_mfma_f32_16x16x32_bf16 v[76:79], v[150:153], v[210:213], v[76:79]
	v_mfma_f32_16x16x32_bf16 v[68:71], v[158:161], v[210:213], v[68:71]
	s_setprio 0
	s_setprio 1
	v_mfma_f32_16x16x32_bf16 v[122:125], v[162:165], v[178:181], v[122:125]
	v_mfma_f32_16x16x32_bf16 v[114:117], v[170:173], v[178:181], v[114:117]
	v_mfma_f32_16x16x32_bf16 v[106:109], v[162:165], v[186:189], v[106:109]
	v_mfma_f32_16x16x32_bf16 v[98:101], v[170:173], v[186:189], v[98:101]
	v_mfma_f32_16x16x32_bf16 v[88:91], v[162:165], v[194:197], v[88:91]
	v_mfma_f32_16x16x32_bf16 v[80:83], v[170:173], v[194:197], v[80:83]
	v_mfma_f32_16x16x32_bf16 v[72:75], v[162:165], v[206:209], v[72:75]
	v_mfma_f32_16x16x32_bf16 v[64:67], v[170:173], v[206:209], v[64:67]
	v_mfma_f32_16x16x32_bf16 v[122:125], v[166:169], v[182:185], v[122:125]
	v_mfma_f32_16x16x32_bf16 v[114:117], v[174:177], v[182:185], v[114:117]
	v_mfma_f32_16x16x32_bf16 v[106:109], v[166:169], v[190:193], v[106:109]
	v_mfma_f32_16x16x32_bf16 v[98:101], v[174:177], v[190:193], v[98:101]
	v_mfma_f32_16x16x32_bf16 v[88:91], v[166:169], v[200:203], v[88:91]
	v_mfma_f32_16x16x32_bf16 v[80:83], v[174:177], v[200:203], v[80:83]
	v_mfma_f32_16x16x32_bf16 v[72:75], v[166:169], v[210:213], v[72:75]
	v_mfma_f32_16x16x32_bf16 v[64:67], v[174:177], v[210:213], v[64:67]
	s_setprio 0
	s_barrier
	s_add_i32 s28, s30, s21
	s_mov_b32 m0, s28
	ds_read_b128 v[178:181], v144 offset:16384
	ds_read_b128 v[182:185], v144 offset:17408
	ds_read_b128 v[186:189], v144 offset:18432
	ds_read_b128 v[190:193], v144 offset:19456
	ds_read_b128 v[194:197], v144 offset:20480
	ds_read_b128 v[200:203], v144 offset:21504
	ds_read_b128 v[206:209], v144 offset:22528
	ds_read_b128 v[210:213], v144 offset:23552
	global_load_lds_dwordx4 v134, s[64:65]
	s_add_i32 m0, s28, 0x2000
	s_add_u32 s28, s64, 0x80000
	s_addc_u32 s29, s65, 0
	s_add_i32 s30, s31, s21
	global_load_lds_dwordx4 v130, s[64:65]
	s_mov_b32 m0, s30
	s_nop 0
	global_load_lds_dwordx4 v134, s[28:29]
	s_add_i32 m0, s30, 0x2000
	s_nop 0
	global_load_lds_dwordx4 v130, s[28:29]
	s_mov_b32 m0, s22
	s_nop 0
	global_load_lds_dwordx4 v136, s[66:67]
	s_mov_b32 m0, s23
	s_nop 0
	global_load_lds_dwordx4 v132, s[66:67]
	s_waitcnt vmcnt(8)
	s_waitcnt lgkmcnt(0)
	s_barrier
	s_setprio 1
	s_waitcnt lgkmcnt(0)
	v_mfma_f32_16x16x32_bf16 v[60:63], v[146:149], v[178:181], v[60:63]
	v_mfma_f32_16x16x32_bf16 v[52:55], v[154:157], v[178:181], v[52:55]
	v_mfma_f32_16x16x32_bf16 v[44:47], v[146:149], v[186:189], v[44:47]
	v_mfma_f32_16x16x32_bf16 v[36:39], v[154:157], v[186:189], v[36:39]
	v_mfma_f32_16x16x32_bf16 v[28:31], v[146:149], v[194:197], v[28:31]
	v_mfma_f32_16x16x32_bf16 v[20:23], v[154:157], v[194:197], v[20:23]
	v_mfma_f32_16x16x32_bf16 v[12:15], v[146:149], v[206:209], v[12:15]
	v_mfma_f32_16x16x32_bf16 v[4:7], v[154:157], v[206:209], v[4:7]
	v_mfma_f32_16x16x32_bf16 v[60:63], v[150:153], v[182:185], v[60:63]
	v_mfma_f32_16x16x32_bf16 v[52:55], v[158:161], v[182:185], v[52:55]
	v_mfma_f32_16x16x32_bf16 v[44:47], v[150:153], v[190:193], v[44:47]
	v_mfma_f32_16x16x32_bf16 v[36:39], v[158:161], v[190:193], v[36:39]
	v_mfma_f32_16x16x32_bf16 v[28:31], v[150:153], v[200:203], v[28:31]
	v_mfma_f32_16x16x32_bf16 v[20:23], v[158:161], v[200:203], v[20:23]
	v_mfma_f32_16x16x32_bf16 v[12:15], v[150:153], v[210:213], v[12:15]
	v_mfma_f32_16x16x32_bf16 v[4:7], v[158:161], v[210:213], v[4:7]
	s_setprio 0
	s_setprio 1
	v_mfma_f32_16x16x32_bf16 v[56:59], v[162:165], v[178:181], v[56:59]
	v_mfma_f32_16x16x32_bf16 v[48:51], v[170:173], v[178:181], v[48:51]
	v_mfma_f32_16x16x32_bf16 v[40:43], v[162:165], v[186:189], v[40:43]
	v_mfma_f32_16x16x32_bf16 v[32:35], v[170:173], v[186:189], v[32:35]
	v_mfma_f32_16x16x32_bf16 v[24:27], v[162:165], v[194:197], v[24:27]
	v_mfma_f32_16x16x32_bf16 v[16:19], v[170:173], v[194:197], v[16:19]
	v_mfma_f32_16x16x32_bf16 v[8:11], v[162:165], v[206:209], v[8:11]
	v_mfma_f32_16x16x32_bf16 v[0:3], v[170:173], v[206:209], v[0:3]
	v_mfma_f32_16x16x32_bf16 v[56:59], v[166:169], v[182:185], v[56:59]
	v_mfma_f32_16x16x32_bf16 v[48:51], v[174:177], v[182:185], v[48:51]
	v_mfma_f32_16x16x32_bf16 v[40:43], v[166:169], v[190:193], v[40:43]
	v_mfma_f32_16x16x32_bf16 v[32:35], v[174:177], v[190:193], v[32:35]
	v_mfma_f32_16x16x32_bf16 v[24:27], v[166:169], v[200:203], v[24:27]
	v_mfma_f32_16x16x32_bf16 v[16:19], v[174:177], v[200:203], v[16:19]
	v_mfma_f32_16x16x32_bf16 v[8:11], v[166:169], v[210:213], v[8:11]
	v_mfma_f32_16x16x32_bf16 v[0:3], v[174:177], v[210:213], v[0:3]
	s_setprio 0
	s_barrier
; #define PG8_STAGE(bufoff, gbase, voff) do { _Pragma("unroll") for (int _i = 0; _i < 2; ++_i) \
;         __builtin_amdgcn_global_load_lds((const unsigned*)((const char*)(gbase) + (voff)[_i]), (PG8_LAS unsigned*)(lds + (bufoff) + ldsw + _i * 8192), 16, 0, 0); } while (0)
; #define PG8_LDA(dst, b, h) do { _Pragma("unroll") for (int m = 0; m < 4; ++m) _Pragma("unroll") for (int k = 0; k < 2; ++k) dst[m][k] = *(const PG8_LAS bf16x8*)(lds + PG8_SA(b, h) + aoff + m * 2048 + k * 1024); } while (0)
; #define PG8_LDB(dst, b, h) do { _Pragma("unroll") for (int n = 0; n < 2; ++n) _Pragma("unroll") for (int k = 0; k < 2; ++k) dst[n][k] = *(const PG8_LAS bf16x8*)(lds + PG8_SB(b, h) + boff + n * 2048 + k * 1024); } while (0)
; #define PG8_MMA(ai, bj, At, Bt) do { __builtin_amdgcn_s_setprio(1); _Pragma("unroll") for (int m = 0; m < 4; ++m) _Pragma("unroll") for (int n = 0; n < 2; ++n) _Pragma("unroll") for (int k = 0; k < 2; ++k) \
;         acc[ai][bj][m][n] = __builtin_amdgcn_mfma_f32_16x16x32_bf16(Bt[n][k], At[m][k], acc[ai][bj][m][n], 0, 0, 0); __builtin_amdgcn_s_setprio(0); } while (0)
; #define PG8_WAIT_V(n) asm volatile("s_waitcnt vmcnt(" #n ")" ::: "memory")
; #define PG8_WAIT_L(n) asm volatile("s_waitcnt lgkmcnt(" #n ")" ::: "memory")
; #define PG8_BAR __builtin_amdgcn_s_barrier()
; #define PG8_SCHED __builtin_amdgcn_sched_barrier(0)
; template <class Epi, class Sched, bool ALIGN_EPI = true, bool SP2 = true>
; __device__ __forceinline__ void gemm_phase(PG8_LAS unsigned char* lds, const Gemm g, const Sched& S, const Epi& E, const int tid) {
;     ...
;             PG8_LDB(B0, 1, 0); PG8_LDB(B1, 1, 1); PG8_SCHED; PG8_LDA(At, 1, 0); PG8_STAGE(PG8_SA(0, 1), a2 + hstepA, voffA);
;             PG8_WAIT_V(8); PG8_WAIT_L(0); PG8_BAR; PG8_MMA(0, 0, At, B0); PG8_MMA(0, 1, At, B1); PG8_BAR; PG8_SCHED;
;             PG8_LDA(At, 1, 1); PG8_STAGE(PG8_SB(1, 0), b3, voffB); PG8_STAGE(PG8_SB(1, 1), b3 + hstepB, voffB); PG8_STAGE(PG8_SA(1, 0), a3, voffA);
;             PG8_WAIT_V(8); PG8_WAIT_L(0); PG8_BAR; PG8_MMA(1, 0, At, B0); PG8_MMA(1, 1, At, B1); PG8_BAR; PG8_SCHED;
	s_add_i32 s30, 0, 0x18000
	v_add_u32_e32 v145, s30, v142
	s_add_i32 s31, 0, 0x1c000
	ds_read_b128 v[146:149], v145
	ds_read_b128 v[150:153], v145 offset:1024
	ds_read_b128 v[154:157], v145 offset:2048
	ds_read_b128 v[158:161], v145 offset:3072
	v_add_u32_e32 v145, s31, v142
	ds_read_b128 v[162:165], v145
	ds_read_b128 v[166:169], v145 offset:1024
	ds_read_b128 v[170:173], v145 offset:2048
	ds_read_b128 v[174:177], v145 offset:3072
	s_add_u32 s28, s66, 0x80000
	s_addc_u32 s29, s67, 0
	s_mov_b32 m0, s61
	ds_read_b128 v[178:181], v144 offset:32768
	ds_read_b128 v[182:185], v144 offset:33792
	ds_read_b128 v[186:189], v144 offset:34816
	ds_read_b128 v[190:193], v144 offset:35840
	ds_read_b128 v[194:197], v144 offset:36864
	ds_read_b128 v[200:203], v144 offset:37888
	ds_read_b128 v[206:209], v144 offset:38912
	ds_read_b128 v[210:213], v144 offset:39936
	global_load_lds_dwordx4 v136, s[28:29]
	s_mov_b32 m0, s70
	s_nop 0
	global_load_lds_dwordx4 v132, s[28:29]
	s_waitcnt vmcnt(8)
	s_waitcnt lgkmcnt(0)
	s_barrier
	s_setprio 1
	s_waitcnt lgkmcnt(0)
	v_mfma_f32_16x16x32_bf16 v[126:129], v[146:149], v[178:181], v[126:129]
	v_mfma_f32_16x16x32_bf16 v[118:121], v[154:157], v[178:181], v[118:121]
	v_mfma_f32_16x16x32_bf16 v[110:113], v[146:149], v[186:189], v[110:113]
	v_mfma_f32_16x16x32_bf16 v[102:105], v[154:157], v[186:189], v[102:105]
	v_mfma_f32_16x16x32_bf16 v[92:95], v[146:149], v[194:197], v[92:95]
	v_mfma_f32_16x16x32_bf16 v[84:87], v[154:157], v[194:197], v[84:87]
	v_mfma_f32_16x16x32_bf16 v[76:79], v[146:149], v[206:209], v[76:79]
	v_mfma_f32_16x16x32_bf16 v[68:71], v[154:157], v[206:209], v[68:71]
	v_mfma_f32_16x16x32_bf16 v[126:129], v[150:153], v[182:185], v[126:129]
	v_mfma_f32_16x16x32_bf16 v[118:121], v[158:161], v[182:185], v[118:121]
	v_mfma_f32_16x16x32_bf16 v[110:113], v[150:153], v[190:193], v[110:113]
	v_mfma_f32_16x16x32_bf16 v[102:105], v[158:161], v[190:193], v[102:105]
	v_mfma_f32_16x16x32_bf16 v[92:95], v[150:153], v[200:203], v[92:95]
	v_mfma_f32_16x16x32_bf16 v[84:87], v[158:161], v[200:203], v[84:87]
	v_mfma_f32_16x16x32_bf16 v[76:79], v[150:153], v[210:213], v[76:79]
	v_mfma_f32_16x16x32_bf16 v[68:71], v[158:161], v[210:213], v[68:71]
	s_setprio 0
	s_setprio 1
	v_mfma_f32_16x16x32_bf16 v[122:125], v[162:165], v[178:181], v[122:125]
	v_mfma_f32_16x16x32_bf16 v[114:117], v[170:173], v[178:181], v[114:117]
	v_mfma_f32_16x16x32_bf16 v[106:109], v[162:165], v[186:189], v[106:109]
	v_mfma_f32_16x16x32_bf16 v[98:101], v[170:173], v[186:189], v[98:101]
	v_mfma_f32_16x16x32_bf16 v[88:91], v[162:165], v[194:197], v[88:91]
	v_mfma_f32_16x16x32_bf16 v[80:83], v[170:173], v[194:197], v[80:83]
	v_mfma_f32_16x16x32_bf16 v[72:75], v[162:165], v[206:209], v[72:75]
	v_mfma_f32_16x16x32_bf16 v[64:67], v[170:173], v[206:209], v[64:67]
	v_mfma_f32_16x16x32_bf16 v[122:125], v[166:169], v[182:185], v[122:125]
	v_mfma_f32_16x16x32_bf16 v[114:117], v[174:177], v[182:185], v[114:117]
	v_mfma_f32_16x16x32_bf16 v[106:109], v[166:169], v[190:193], v[106:109]
	v_mfma_f32_16x16x32_bf16 v[98:101], v[174:177], v[190:193], v[98:101]
	v_mfma_f32_16x16x32_bf16 v[88:91], v[166:169], v[200:203], v[88:91]
	v_mfma_f32_16x16x32_bf16 v[80:83], v[174:177], v[200:203], v[80:83]
	v_mfma_f32_16x16x32_bf16 v[72:75], v[166:169], v[210:213], v[72:75]
	v_mfma_f32_16x16x32_bf16 v[64:67], v[174:177], v[210:213], v[64:67]
	s_setprio 0
	s_barrier
	s_add_i32 s28, s30, s21
	s_add_u32 s4, s64, 0x80
	s_addc_u32 s5, s65, 0
	s_mov_b32 m0, s28
	ds_read_b128 v[178:181], v144 offset:49152
	ds_read_b128 v[182:185], v144 offset:50176
	ds_read_b128 v[186:189], v144 offset:51200
	ds_read_b128 v[190:193], v144 offset:52224
	ds_read_b128 v[194:197], v144 offset:53248
	ds_read_b128 v[200:203], v144 offset:54272
	ds_read_b128 v[206:209], v144 offset:55296
	ds_read_b128 v[210:213], v144 offset:56320
	global_load_lds_dwordx4 v134, s[4:5]
	s_add_i32 m0, s28, 0x2000
	s_add_u32 s28, s64, 0x80080
	s_addc_u32 s29, s65, 0
	s_add_i32 s30, s31, s21
	global_load_lds_dwordx4 v130, s[4:5]
	s_mov_b32 m0, s30
	s_nop 0
	global_load_lds_dwordx4 v134, s[28:29]
	s_add_i32 m0, s30, 0x2000
	s_nop 0
	global_load_lds_dwordx4 v130, s[28:29]
	s_add_u32 s4, s66, 0x80
	s_addc_u32 s5, s67, 0
	s_mov_b32 m0, s71
	s_nop 0
	global_load_lds_dwordx4 v136, s[4:5]
	s_mov_b32 m0, s72
	s_nop 0
	global_load_lds_dwordx4 v132, s[4:5]
	s_waitcnt vmcnt(8)
	s_waitcnt lgkmcnt(0)
	s_barrier
	s_setprio 1
	s_waitcnt lgkmcnt(0)
	v_mfma_f32_16x16x32_bf16 v[60:63], v[146:149], v[178:181], v[60:63]
	v_mfma_f32_16x16x32_bf16 v[52:55], v[154:157], v[178:181], v[52:55]
	v_mfma_f32_16x16x32_bf16 v[44:47], v[146:149], v[186:189], v[44:47]
	v_mfma_f32_16x16x32_bf16 v[36:39], v[154:157], v[186:189], v[36:39]
	v_mfma_f32_16x16x32_bf16 v[28:31], v[146:149], v[194:197], v[28:31]
	v_mfma_f32_16x16x32_bf16 v[20:23], v[154:157], v[194:197], v[20:23]
	v_mfma_f32_16x16x32_bf16 v[12:15], v[146:149], v[206:209], v[12:15]
	v_mfma_f32_16x16x32_bf16 v[4:7], v[154:157], v[206:209], v[4:7]
	v_mfma_f32_16x16x32_bf16 v[60:63], v[150:153], v[182:185], v[60:63]
	v_mfma_f32_16x16x32_bf16 v[52:55], v[158:161], v[182:185], v[52:55]
	v_mfma_f32_16x16x32_bf16 v[44:47], v[150:153], v[190:193], v[44:47]
	v_mfma_f32_16x16x32_bf16 v[36:39], v[158:161], v[190:193], v[36:39]
	v_mfma_f32_16x16x32_bf16 v[28:31], v[150:153], v[200:203], v[28:31]
	v_mfma_f32_16x16x32_bf16 v[20:23], v[158:161], v[200:203], v[20:23]
	v_mfma_f32_16x16x32_bf16 v[12:15], v[150:153], v[210:213], v[12:15]
	v_mfma_f32_16x16x32_bf16 v[4:7], v[158:161], v[210:213], v[4:7]
	s_setprio 0
	s_setprio 1
	v_mfma_f32_16x16x32_bf16 v[56:59], v[162:165], v[178:181], v[56:59]
	v_mfma_f32_16x16x32_bf16 v[48:51], v[170:173], v[178:181], v[48:51]
	v_mfma_f32_16x16x32_bf16 v[40:43], v[162:165], v[186:189], v[40:43]
	v_mfma_f32_16x16x32_bf16 v[32:35], v[170:173], v[186:189], v[32:35]
	v_mfma_f32_16x16x32_bf16 v[24:27], v[162:165], v[194:197], v[24:27]
	v_mfma_f32_16x16x32_bf16 v[16:19], v[170:173], v[194:197], v[16:19]
	v_mfma_f32_16x16x32_bf16 v[8:11], v[162:165], v[206:209], v[8:11]
	v_mfma_f32_16x16x32_bf16 v[0:3], v[170:173], v[206:209], v[0:3]
	v_mfma_f32_16x16x32_bf16 v[56:59], v[166:169], v[182:185], v[56:59]
	v_mfma_f32_16x16x32_bf16 v[48:51], v[174:177], v[182:185], v[48:51]
	v_mfma_f32_16x16x32_bf16 v[40:43], v[166:169], v[190:193], v[40:43]
	v_mfma_f32_16x16x32_bf16 v[32:35], v[174:177], v[190:193], v[32:35]
	v_mfma_f32_16x16x32_bf16 v[24:27], v[166:169], v[200:203], v[24:27]
	v_mfma_f32_16x16x32_bf16 v[16:19], v[174:177], v[200:203], v[16:19]
	v_mfma_f32_16x16x32_bf16 v[8:11], v[166:169], v[210:213], v[8:11]
	v_mfma_f32_16x16x32_bf16 v[0:3], v[174:177], v[210:213], v[0:3]
	s_setprio 0
	s_barrier
	s_add_i32 s52, s52, 2
	s_add_u32 s62, s62, 0x100
	s_addc_u32 s63, s63, 0
	s_add_u32 s49, s49, 0x100
	s_addc_u32 s51, s51, 0
	s_cmp_gt_u32 s52, 29
	s_cbranch_scc0 .LBB0_1319
	s_mov_b64 s[4:5], 0x80
	s_and_b64 vcc, exec, s[46:47]
	s_cbranch_vccz .LBB0_1322
	s_barrier

; #define PG8_STAGE(bufoff, gbase, voff) do { _Pragma("unroll") for (int _i = 0; _i < 2; ++_i) \
;         __builtin_amdgcn_global_load_lds((const unsigned*)((const char*)(gbase) + (voff)[_i]), (PG8_LAS unsigned*)(lds + (bufoff) + ldsw + _i * 8192), 16, 0, 0); } while (0)
; #define PG8_LDA(dst, b, h) do { _Pragma("unroll") for (int m = 0; m < 4; ++m) _Pragma("unroll") for (int k = 0; k < 2; ++k) dst[m][k] = *(const PG8_LAS bf16x8*)(lds + PG8_SA(b, h) + aoff + m * 2048 + k * 1024); } while (0)
; #define PG8_LDB(dst, b, h) do { _Pragma("unroll") for (int n = 0; n < 2; ++n) _Pragma("unroll") for (int k = 0; k < 2; ++k) dst[n][k] = *(const PG8_LAS bf16x8*)(lds + PG8_SB(b, h) + boff + n * 2048 + k * 1024); } while (0)
; #define PG8_MMA(ai, bj, At, Bt) do { __builtin_amdgcn_s_setprio(1); _Pragma("unroll") for (int m = 0; m < 4; ++m) _Pragma("unroll") for (int n = 0; n < 2; ++n) _Pragma("unroll") for (int k = 0; k < 2; ++k) \
;         acc[ai][bj][m][n] = __builtin_amdgcn_mfma_f32_16x16x32_bf16(Bt[n][k], At[m][k], acc[ai][bj][m][n], 0, 0, 0); __builtin_amdgcn_s_setprio(0); } while (0)
; #define PG8_WAIT_V(n) asm volatile("s_waitcnt vmcnt(" #n ")" ::: "memory")
; #define PG8_WAIT_L(n) asm volatile("s_waitcnt lgkmcnt(" #n ")" ::: "memory")
; template <class Epi, class Sched, bool ALIGN_EPI = true, bool SP2 = true>
; __device__ __forceinline__ void gemm_phase(PG8_LAS unsigned char* lds, const Gemm g, const Sched& S, const Epi& E, const int tid) {
;     ...
;             const bool last = (t == nt - 2);
;             const char* a1 = cA + (size_t)(t + 1) * kstep;
;             const char* a2 = last ? nA : cA + (size_t)(t + 2) * kstep; const char* b2 = last ? nB : cB + (size_t)(t + 2) * kstep;
;             const char* a3 = a2 + kstep; const char* b3 = b2 + kstep;
;             if (last && has_next) S.a_ready(nxt);
;             if constexpr (SP2) {
;             PG8_LDB(B0, 0, 0); PG8_LDB(B1, 0, 1); PG8_SCHED; PG8_LDA(At, 0, 0); PG8_STAGE(PG8_SA(1, 1), a1 + hstepA, voffA);
;             PG8_WAIT_V(8); PG8_WAIT_L(0); PG8_BAR; PG8_MMA(0, 0, At, B0); PG8_MMA(0, 1, At, B1); PG8_BAR; PG8_SCHED;
;             PG8_LDA(At, 0, 1); PG8_STAGE(PG8_SB(0, 0), b2, voffB); PG8_STAGE(PG8_SB(0, 1), b2 + hstepB, voffB); PG8_STAGE(PG8_SA(0, 0), a2, voffA);
;             PG8_WAIT_V(8); PG8_WAIT_L(0); PG8_BAR; PG8_MMA(1, 0, At, B0); PG8_MMA(1, 1, At, B1); PG8_BAR; PG8_SCHED;
.LBB0_1523:
	s_add_i32 vcc_lo, s72, 2
	s_add_u32 s70, s82, 0x100
	s_addc_u32 s71, s83, 0
	s_add_i32 s30, 0, 0x10000
	s_cmp_eq_u32 s29, s72
	s_cselect_b32 s81, s63, s71
	s_cselect_b32 s80, s62, s70
	v_add_u32_e32 v96, s30, v141
	s_cselect_b32 s73, s65, s59
	s_cselect_b32 s72, s64, s57
	s_add_i32 s31, 0, 0x14000
	ds_read_b128 v[146:149], v96
	ds_read_b128 v[150:153], v96 offset:1024
	ds_read_b128 v[154:157], v96 offset:2048
	ds_read_b128 v[158:161], v96 offset:3072
	v_add_u32_e32 v96, s31, v141
	ds_read_b128 v[162:165], v96
	ds_read_b128 v[166:169], v96 offset:1024
	ds_read_b128 v[170:173], v96 offset:2048
	ds_read_b128 v[174:177], v96 offset:3072
	s_add_i32 m0, s23, 0xc000
	ds_read_b128 v[178:181], v145
	ds_read_b128 v[182:185], v145 offset:1024
	ds_read_b128 v[186:189], v145 offset:2048
	ds_read_b128 v[190:193], v145 offset:3072
	ds_read_b128 v[194:197], v145 offset:4096
	ds_read_b128 v[200:203], v145 offset:5120
	ds_read_b128 v[206:209], v145 offset:6144
	ds_read_b128 v[210:213], v145 offset:7168
	global_load_lds_dwordx4 v136, s[82:83]
	s_add_i32 m0, s23, 0xe000
	s_nop 0
	global_load_lds_dwordx4 v138, s[82:83]
	s_waitcnt vmcnt(8)
	s_waitcnt lgkmcnt(0)
	s_barrier
	s_setprio 1
	s_waitcnt lgkmcnt(0)
	v_mfma_f32_16x16x32_bf16 v[52:55], v[146:149], v[178:181], v[52:55]
	v_mfma_f32_16x16x32_bf16 v[56:59], v[154:157], v[178:181], v[56:59]
	v_mfma_f32_16x16x32_bf16 v[104:107], v[146:149], v[186:189], v[104:107]
	v_mfma_f32_16x16x32_bf16 v[84:87], v[154:157], v[186:189], v[84:87]
	v_mfma_f32_16x16x32_bf16 v[110:113], v[146:149], v[194:197], v[110:113]
	v_mfma_f32_16x16x32_bf16 v[98:101], v[154:157], v[194:197], v[100:103]
	v_mfma_f32_16x16x32_bf16 v[88:91], v[146:149], v[206:209], v[88:91]
	v_mfma_f32_16x16x32_bf16 v[80:83], v[154:157], v[206:209], v[80:83]
	v_mfma_f32_16x16x32_bf16 v[52:55], v[150:153], v[182:185], v[52:55]
	v_mfma_f32_16x16x32_bf16 v[56:59], v[158:161], v[182:185], v[56:59]
	v_mfma_f32_16x16x32_bf16 v[104:107], v[150:153], v[190:193], v[104:107]
	v_mfma_f32_16x16x32_bf16 v[84:87], v[158:161], v[190:193], v[84:87]
	v_mfma_f32_16x16x32_bf16 v[110:113], v[150:153], v[200:203], v[110:113]
	v_mfma_f32_16x16x32_bf16 v[98:101], v[158:161], v[200:203], v[98:101]
	v_mfma_f32_16x16x32_bf16 v[88:91], v[150:153], v[210:213], v[88:91]
	v_mfma_f32_16x16x32_bf16 v[80:83], v[158:161], v[210:213], v[80:83]
	s_setprio 0
	s_setprio 1
	v_mfma_f32_16x16x32_bf16 v[48:51], v[162:165], v[178:181], v[48:51]
	v_mfma_f32_16x16x32_bf16 v[44:47], v[170:173], v[178:181], v[44:47]
	v_mfma_f32_16x16x32_bf16 v[76:79], v[162:165], v[186:189], v[76:79]
	v_mfma_f32_16x16x32_bf16 v[68:71], v[170:173], v[186:189], v[68:71]
	v_mfma_f32_16x16x32_bf16 v[130:133], v[162:165], v[194:197], v[130:133]
	v_mfma_f32_16x16x32_bf16 v[92:95], v[170:173], v[194:197], v[92:95]
	v_mfma_f32_16x16x32_bf16 v[72:75], v[162:165], v[206:209], v[72:75]
	v_mfma_f32_16x16x32_bf16 v[64:67], v[170:173], v[206:209], v[64:67]
	v_mfma_f32_16x16x32_bf16 v[48:51], v[166:169], v[182:185], v[48:51]
	v_mfma_f32_16x16x32_bf16 v[44:47], v[174:177], v[182:185], v[44:47]
	v_mfma_f32_16x16x32_bf16 v[76:79], v[166:169], v[190:193], v[76:79]
	v_mfma_f32_16x16x32_bf16 v[68:71], v[174:177], v[190:193], v[68:71]
	v_mfma_f32_16x16x32_bf16 v[130:133], v[166:169], v[200:203], v[130:133]
	v_mfma_f32_16x16x32_bf16 v[92:95], v[174:177], v[200:203], v[92:95]
	v_mfma_f32_16x16x32_bf16 v[72:75], v[166:169], v[210:213], v[72:75]
	v_mfma_f32_16x16x32_bf16 v[64:67], v[174:177], v[210:213], v[64:67]
	s_setprio 0
	s_barrier
	s_add_i32 s30, s30, s22
	s_mov_b32 m0, s30
	ds_read_b128 v[178:181], v145 offset:16384
	ds_read_b128 v[182:185], v145 offset:17408
	ds_read_b128 v[186:189], v145 offset:18432
	ds_read_b128 v[190:193], v145 offset:19456
	ds_read_b128 v[194:197], v145 offset:20480
	ds_read_b128 v[200:203], v145 offset:21504
	ds_read_b128 v[206:209], v145 offset:22528
	ds_read_b128 v[210:213], v145 offset:23552
	global_load_lds_dwordx4 v108, s[72:73]
	s_add_i32 m0, s30, 0x2000
	s_add_u32 s82, s72, 0x160000
	s_addc_u32 s83, s73, 0
	s_add_i32 s30, s31, s22
	global_load_lds_dwordx4 v134, s[72:73]
	s_mov_b32 m0, s30
	s_nop 0
	global_load_lds_dwordx4 v108, s[82:83]
	s_add_i32 m0, s30, 0x2000
	s_nop 0
	global_load_lds_dwordx4 v134, s[82:83]
	s_mov_b32 m0, s23
	s_nop 0
	global_load_lds_dwordx4 v108, s[80:81]
	s_mov_b32 m0, s24
	s_nop 0
	global_load_lds_dwordx4 v134, s[80:81]
	s_waitcnt vmcnt(8)
	s_waitcnt lgkmcnt(0)
	s_barrier
	s_setprio 1
	s_waitcnt lgkmcnt(0)
	v_mfma_f32_16x16x32_bf16 v[126:129], v[146:149], v[178:181], v[126:129]
	v_mfma_f32_16x16x32_bf16 v[122:125], v[154:157], v[178:181], v[122:125]
	v_mfma_f32_16x16x32_bf16 v[60:63], v[146:149], v[186:189], v[60:63]
	v_mfma_f32_16x16x32_bf16 v[40:43], v[154:157], v[186:189], v[40:43]
	v_mfma_f32_16x16x32_bf16 v[28:31], v[146:149], v[194:197], v[28:31]
	v_mfma_f32_16x16x32_bf16 v[24:27], v[154:157], v[194:197], v[24:27]
	v_mfma_f32_16x16x32_bf16 v[12:15], v[146:149], v[206:209], v[12:15]
	v_mfma_f32_16x16x32_bf16 v[8:11], v[154:157], v[206:209], v[8:11]
	v_mfma_f32_16x16x32_bf16 v[126:129], v[150:153], v[182:185], v[126:129]
	v_mfma_f32_16x16x32_bf16 v[122:125], v[158:161], v[182:185], v[122:125]
	v_mfma_f32_16x16x32_bf16 v[60:63], v[150:153], v[190:193], v[60:63]
	v_mfma_f32_16x16x32_bf16 v[40:43], v[158:161], v[190:193], v[40:43]
	v_mfma_f32_16x16x32_bf16 v[28:31], v[150:153], v[200:203], v[28:31]
	v_mfma_f32_16x16x32_bf16 v[24:27], v[158:161], v[200:203], v[24:27]
	v_mfma_f32_16x16x32_bf16 v[12:15], v[150:153], v[210:213], v[12:15]
	v_mfma_f32_16x16x32_bf16 v[8:11], v[158:161], v[210:213], v[8:11]
	s_setprio 0
	s_setprio 1
	v_mfma_f32_16x16x32_bf16 v[118:121], v[162:165], v[178:181], v[118:121]
	v_mfma_f32_16x16x32_bf16 v[114:117], v[170:173], v[178:181], v[114:117]
	v_mfma_f32_16x16x32_bf16 v[36:39], v[162:165], v[186:189], v[36:39]
	v_mfma_f32_16x16x32_bf16 v[32:35], v[170:173], v[186:189], v[32:35]
	v_mfma_f32_16x16x32_bf16 v[20:23], v[162:165], v[194:197], v[20:23]
	v_mfma_f32_16x16x32_bf16 v[16:19], v[170:173], v[194:197], v[16:19]
	v_mfma_f32_16x16x32_bf16 v[4:7], v[162:165], v[206:209], v[4:7]
	v_mfma_f32_16x16x32_bf16 v[0:3], v[170:173], v[206:209], v[0:3]
	v_mfma_f32_16x16x32_bf16 v[118:121], v[166:169], v[182:185], v[118:121]
	v_mfma_f32_16x16x32_bf16 v[114:117], v[174:177], v[182:185], v[114:117]
	v_mfma_f32_16x16x32_bf16 v[36:39], v[166:169], v[190:193], v[36:39]
	v_mfma_f32_16x16x32_bf16 v[32:35], v[174:177], v[190:193], v[32:35]
	v_mfma_f32_16x16x32_bf16 v[20:23], v[166:169], v[200:203], v[20:23]
	v_mfma_f32_16x16x32_bf16 v[16:19], v[174:177], v[200:203], v[16:19]
	v_mfma_f32_16x16x32_bf16 v[4:7], v[166:169], v[210:213], v[4:7]
	v_mfma_f32_16x16x32_bf16 v[0:3], v[174:177], v[210:213], v[0:3]
	s_setprio 0
	s_barrier
; #define PG8_STAGE(bufoff, gbase, voff) do { _Pragma("unroll") for (int _i = 0; _i < 2; ++_i) \
;         __builtin_amdgcn_global_load_lds((const unsigned*)((const char*)(gbase) + (voff)[_i]), (PG8_LAS unsigned*)(lds + (bufoff) + ldsw + _i * 8192), 16, 0, 0); } while (0)
; #define PG8_LDA(dst, b, h) do { _Pragma("unroll") for (int m = 0; m < 4; ++m) _Pragma("unroll") for (int k = 0; k < 2; ++k) dst[m][k] = *(const PG8_LAS bf16x8*)(lds + PG8_SA(b, h) + aoff + m * 2048 + k * 1024); } while (0)
; #define PG8_LDB(dst, b, h) do { _Pragma("unroll") for (int n = 0; n < 2; ++n) _Pragma("unroll") for (int k = 0; k < 2; ++k) dst[n][k] = *(const PG8_LAS bf16x8*)(lds + PG8_SB(b, h) + boff + n * 2048 + k * 1024); } while (0)
; #define PG8_MMA(ai, bj, At, Bt) do { __builtin_amdgcn_s_setprio(1); _Pragma("unroll") for (int m = 0; m < 4; ++m) _Pragma("unroll") for (int n = 0; n < 2; ++n) _Pragma("unroll") for (int k = 0; k < 2; ++k) \
;         acc[ai][bj][m][n] = __builtin_amdgcn_mfma_f32_16x16x32_bf16(Bt[n][k], At[m][k], acc[ai][bj][m][n], 0, 0, 0); __builtin_amdgcn_s_setprio(0); } while (0)
; #define PG8_WAIT_V(n) asm volatile("s_waitcnt vmcnt(" #n ")" ::: "memory")
; #define PG8_WAIT_L(n) asm volatile("s_waitcnt lgkmcnt(" #n ")" ::: "memory")
; #define PG8_BAR __builtin_amdgcn_s_barrier()
; #define PG8_SCHED __builtin_amdgcn_sched_barrier(0)
; template <class Epi, class Sched, bool ALIGN_EPI = true, bool SP2 = true>
; __device__ __forceinline__ void gemm_phase(PG8_LAS unsigned char* lds, const Gemm g, const Sched& S, const Epi& E, const int tid) {
;     ...
;             PG8_LDB(B0, 1, 0); PG8_LDB(B1, 1, 1); PG8_SCHED; PG8_LDA(At, 1, 0); PG8_STAGE(PG8_SA(0, 1), a2 + hstepA, voffA);
;             PG8_WAIT_V(8); PG8_WAIT_L(0); PG8_BAR; PG8_MMA(0, 0, At, B0); PG8_MMA(0, 1, At, B1); PG8_BAR; PG8_SCHED;
;             PG8_LDA(At, 1, 1); PG8_STAGE(PG8_SB(1, 0), b3, voffB); PG8_STAGE(PG8_SB(1, 1), b3 + hstepB, voffB); PG8_STAGE(PG8_SA(1, 0), a3, voffA);
;             PG8_WAIT_V(8); PG8_WAIT_L(0); PG8_BAR; PG8_MMA(1, 0, At, B0); PG8_MMA(1, 1, At, B1); PG8_BAR; PG8_SCHED;
	s_add_i32 s30, 0, 0x18000
	v_add_u32_e32 v96, s30, v141
	s_add_i32 s31, 0, 0x1c000
	ds_read_b128 v[146:149], v96
	ds_read_b128 v[150:153], v96 offset:1024
	ds_read_b128 v[154:157], v96 offset:2048
	ds_read_b128 v[158:161], v96 offset:3072
	v_add_u32_e32 v96, s31, v141
	ds_read_b128 v[162:165], v96
	ds_read_b128 v[166:169], v96 offset:1024
	ds_read_b128 v[170:173], v96 offset:2048
	ds_read_b128 v[174:177], v96 offset:3072
	s_add_u32 s80, s80, 0x160000
	s_addc_u32 s81, s81, 0
	s_mov_b32 m0, s25
	ds_read_b128 v[178:181], v145 offset:32768
	ds_read_b128 v[182:185], v145 offset:33792
	ds_read_b128 v[186:189], v145 offset:34816
	ds_read_b128 v[190:193], v145 offset:35840
	ds_read_b128 v[194:197], v145 offset:36864
	ds_read_b128 v[200:203], v145 offset:37888
	ds_read_b128 v[206:209], v145 offset:38912
	ds_read_b128 v[210:213], v145 offset:39936
	global_load_lds_dwordx4 v108, s[80:81]
	s_mov_b32 m0, s49
	s_nop 0
	global_load_lds_dwordx4 v134, s[80:81]
	s_waitcnt vmcnt(8)
	s_waitcnt lgkmcnt(0)
	s_barrier
	s_setprio 1
	s_waitcnt lgkmcnt(0)
	v_mfma_f32_16x16x32_bf16 v[52:55], v[146:149], v[178:181], v[52:55]
	v_mfma_f32_16x16x32_bf16 v[56:59], v[154:157], v[178:181], v[56:59]
	v_mfma_f32_16x16x32_bf16 v[102:105], v[146:149], v[186:189], v[104:107]
	v_mfma_f32_16x16x32_bf16 v[84:87], v[154:157], v[186:189], v[84:87]
	v_mfma_f32_16x16x32_bf16 v[110:113], v[146:149], v[194:197], v[110:113]
	v_mfma_f32_16x16x32_bf16 v[98:101], v[154:157], v[194:197], v[98:101]
	v_mfma_f32_16x16x32_bf16 v[88:91], v[146:149], v[206:209], v[88:91]
	v_mfma_f32_16x16x32_bf16 v[80:83], v[154:157], v[206:209], v[80:83]
	v_mfma_f32_16x16x32_bf16 v[52:55], v[150:153], v[182:185], v[52:55]
	v_mfma_f32_16x16x32_bf16 v[56:59], v[158:161], v[182:185], v[56:59]
	v_mfma_f32_16x16x32_bf16 v[104:107], v[150:153], v[190:193], v[102:105]
	v_mfma_f32_16x16x32_bf16 v[84:87], v[158:161], v[190:193], v[84:87]
	v_mfma_f32_16x16x32_bf16 v[110:113], v[150:153], v[200:203], v[110:113]
	v_mfma_f32_16x16x32_bf16 v[100:103], v[158:161], v[200:203], v[98:101]
	v_mfma_f32_16x16x32_bf16 v[88:91], v[150:153], v[210:213], v[88:91]
	v_mfma_f32_16x16x32_bf16 v[80:83], v[158:161], v[210:213], v[80:83]
	s_setprio 0
	s_setprio 1
	v_mfma_f32_16x16x32_bf16 v[48:51], v[162:165], v[178:181], v[48:51]
	v_mfma_f32_16x16x32_bf16 v[44:47], v[170:173], v[178:181], v[44:47]
	v_mfma_f32_16x16x32_bf16 v[76:79], v[162:165], v[186:189], v[76:79]
	v_mfma_f32_16x16x32_bf16 v[68:71], v[170:173], v[186:189], v[68:71]
	v_mfma_f32_16x16x32_bf16 v[130:133], v[162:165], v[194:197], v[130:133]
	v_mfma_f32_16x16x32_bf16 v[92:95], v[170:173], v[194:197], v[92:95]
	v_mfma_f32_16x16x32_bf16 v[72:75], v[162:165], v[206:209], v[72:75]
	v_mfma_f32_16x16x32_bf16 v[64:67], v[170:173], v[206:209], v[64:67]
	v_mfma_f32_16x16x32_bf16 v[48:51], v[166:169], v[182:185], v[48:51]
	v_mfma_f32_16x16x32_bf16 v[44:47], v[174:177], v[182:185], v[44:47]
	v_mfma_f32_16x16x32_bf16 v[76:79], v[166:169], v[190:193], v[76:79]
	v_mfma_f32_16x16x32_bf16 v[68:71], v[174:177], v[190:193], v[68:71]
	v_mfma_f32_16x16x32_bf16 v[130:133], v[166:169], v[200:203], v[130:133]
	v_mfma_f32_16x16x32_bf16 v[92:95], v[174:177], v[200:203], v[92:95]
	v_mfma_f32_16x16x32_bf16 v[72:75], v[166:169], v[210:213], v[72:75]
	v_mfma_f32_16x16x32_bf16 v[64:67], v[174:177], v[210:213], v[64:67]
	s_setprio 0
	s_barrier
	s_add_i32 s30, s30, s22
	s_add_u32 s4, s72, 0x80
	s_addc_u32 s5, s73, 0
	s_mov_b32 m0, s30
	ds_read_b128 v[178:181], v145 offset:49152
	ds_read_b128 v[182:185], v145 offset:50176
	ds_read_b128 v[186:189], v145 offset:51200
	ds_read_b128 v[190:193], v145 offset:52224
	ds_read_b128 v[194:197], v145 offset:53248
	ds_read_b128 v[200:203], v145 offset:54272
	ds_read_b128 v[206:209], v145 offset:55296
	ds_read_b128 v[210:213], v145 offset:56320
	global_load_lds_dwordx4 v108, s[4:5]
	s_add_i32 m0, s30, 0x2000
	s_add_u32 s72, s72, 0x160080
	s_addc_u32 s73, s73, 0
	s_add_i32 s30, s31, s22
	global_load_lds_dwordx4 v134, s[4:5]
	s_mov_b32 m0, s30
	s_nop 0
	global_load_lds_dwordx4 v108, s[72:73]
	s_add_i32 m0, s30, 0x2000
	s_nop 0
	global_load_lds_dwordx4 v134, s[72:73]
	s_add_u32 s4, s80, 0xffea0080
	s_addc_u32 s5, s81, -1
	s_mov_b32 m0, s91
	s_nop 0
	global_load_lds_dwordx4 v108, s[4:5]
	s_mov_b32 m0, s86
	s_nop 0
	global_load_lds_dwordx4 v134, s[4:5]
	s_waitcnt vmcnt(8)
	s_waitcnt lgkmcnt(0)
	s_barrier
	s_setprio 1
	s_waitcnt lgkmcnt(0)
	v_mfma_f32_16x16x32_bf16 v[126:129], v[146:149], v[178:181], v[126:129]
	v_mfma_f32_16x16x32_bf16 v[122:125], v[154:157], v[178:181], v[122:125]
	v_mfma_f32_16x16x32_bf16 v[60:63], v[146:149], v[186:189], v[60:63]
	v_mfma_f32_16x16x32_bf16 v[40:43], v[154:157], v[186:189], v[40:43]
	v_mfma_f32_16x16x32_bf16 v[28:31], v[146:149], v[194:197], v[28:31]
	v_mfma_f32_16x16x32_bf16 v[24:27], v[154:157], v[194:197], v[24:27]
	v_mfma_f32_16x16x32_bf16 v[12:15], v[146:149], v[206:209], v[12:15]
	v_mfma_f32_16x16x32_bf16 v[8:11], v[154:157], v[206:209], v[8:11]
	v_mfma_f32_16x16x32_bf16 v[126:129], v[150:153], v[182:185], v[126:129]
	v_mfma_f32_16x16x32_bf16 v[122:125], v[158:161], v[182:185], v[122:125]
	v_mfma_f32_16x16x32_bf16 v[60:63], v[150:153], v[190:193], v[60:63]
	v_mfma_f32_16x16x32_bf16 v[40:43], v[158:161], v[190:193], v[40:43]
	v_mfma_f32_16x16x32_bf16 v[28:31], v[150:153], v[200:203], v[28:31]
	v_mfma_f32_16x16x32_bf16 v[24:27], v[158:161], v[200:203], v[24:27]
	v_mfma_f32_16x16x32_bf16 v[12:15], v[150:153], v[210:213], v[12:15]
	v_mfma_f32_16x16x32_bf16 v[8:11], v[158:161], v[210:213], v[8:11]
	s_setprio 0
	s_setprio 1
	v_mfma_f32_16x16x32_bf16 v[118:121], v[162:165], v[178:181], v[118:121]
	v_mfma_f32_16x16x32_bf16 v[114:117], v[170:173], v[178:181], v[114:117]
	v_mfma_f32_16x16x32_bf16 v[36:39], v[162:165], v[186:189], v[36:39]
	v_mfma_f32_16x16x32_bf16 v[32:35], v[170:173], v[186:189], v[32:35]
	v_mfma_f32_16x16x32_bf16 v[20:23], v[162:165], v[194:197], v[20:23]
	v_mfma_f32_16x16x32_bf16 v[16:19], v[170:173], v[194:197], v[16:19]
	v_mfma_f32_16x16x32_bf16 v[4:7], v[162:165], v[206:209], v[4:7]
	v_mfma_f32_16x16x32_bf16 v[0:3], v[170:173], v[206:209], v[0:3]
	v_mfma_f32_16x16x32_bf16 v[118:121], v[166:169], v[182:185], v[118:121]
	v_mfma_f32_16x16x32_bf16 v[114:117], v[174:177], v[182:185], v[114:117]
	v_mfma_f32_16x16x32_bf16 v[36:39], v[166:169], v[190:193], v[36:39]
	v_mfma_f32_16x16x32_bf16 v[32:35], v[174:177], v[190:193], v[32:35]
	v_mfma_f32_16x16x32_bf16 v[20:23], v[166:169], v[200:203], v[20:23]
	v_mfma_f32_16x16x32_bf16 v[16:19], v[174:177], v[200:203], v[16:19]
	v_mfma_f32_16x16x32_bf16 v[4:7], v[166:169], v[210:213], v[4:7]
	v_mfma_f32_16x16x32_bf16 v[0:3], v[174:177], v[210:213], v[0:3]
	s_setprio 0
	s_barrier
	s_add_u32 s57, s57, 0x100
	s_addc_u32 s59, s59, 0
	s_cmp_ge_i32 vcc_lo, s53
	s_mov_b64 s[82:83], s[70:71]
	s_mov_b32 s72, vcc_lo
	s_cbranch_scc0 .LBB0_1523
	s_mov_b64 s[4:5], 0x80
